# hgrn stage 3: 16 rows per wave in flight (all loads up front, counted waits), DPP row reductions instead of ds_bpermute; bit-identical math
# speedup vs baseline: 1.0119x; 1.0047x over previous
.LBB0_678:
.LBB0_679:
	v_readlane_b32 s2, v250, 22
	s_cmp_le_i32 s2, s5
	v_readlane_b32 s4, v246, 34
	v_readlane_b32 s3, v250, 23
	v_readlane_b32 s5, v246, 35
	s_cselect_b64 s[2:3], -1, 0
	s_and_b64 s[6:7], s[4:5], s[0:1]
	s_and_b64 s[6:7], s[2:3], s[6:7]
	s_andn2_b64 vcc, exec, s[6:7]
	s_cbranch_vccnz .LBB0_684
	s_waitcnt vmcnt(0)
	v_mov_b32_e32 v10, v216
	v_readlane_b32 s4, v246, 12
	v_ashrrev_i32_e32 v8, 6, v10
	v_readlane_b32 s5, v246, 13
	s_waitcnt vmcnt(16)
	v_add_u32_e32 v12, s4, v8
	v_readlane_b32 s4, v248, 58
	s_nop 1
	v_cmp_gt_i32_e32 vcc, s4, v12
	s_and_saveexec_b64 s[6:7], vcc
	v_readlane_b32 s10, v246, 27
	v_readlane_b32 s11, v246, 28
	v_readlane_b32 s16, v246, 14
	v_readlane_b32 s18, v246, 29
	v_readlane_b32 s17, v246, 15
	s_mov_b32 s11, 0x800000
	v_readlane_b32 s19, v246, 30
	s_cbranch_execz .LBB0_683
	v_readlane_b32 s40, v250, 24
	v_readlane_b32 s4, v246, 38
	v_readlane_b32 s52, v250, 36
	v_readlane_b32 s53, v250, 37
	s_lshl_b32 s24, s4, 9
	v_readlane_b32 s54, v250, 38
	v_readlane_b32 s55, v250, 39
	s_mov_b64 s[12:13], s[52:53]
	s_lshl_b64 s[8:9], s[24:25], 2
	s_mov_b64 s[14:15], s[54:55]
	s_add_u32 s8, s14, s8
	v_lshlrev_b32_e32 v0, 5, v10
	s_addc_u32 s9, s15, s9
	v_and_b32_e32 v4, 0x7e0, v0
	s_waitcnt lgkmcnt(0)
	global_load_dwordx4 v[0:3], v4, s[8:9]
	s_nop 0
	global_load_dwordx4 v[4:7], v4, s[8:9] offset:16
	v_and_b32_e32 v11, 64, v221
	v_xor_b32_e32 v9, 1, v221
	v_add_u32_e32 v11, 64, v11
	v_cmp_lt_i32_e32 vcc, v9, v11
	v_readlane_b32 s4, v246, 12
	v_readlane_b32 s5, v246, 13
	v_cndmask_b32_e32 v9, v221, v9, vcc
	v_lshlrev_b32_e32 v13, 2, v9
	v_xor_b32_e32 v9, 2, v221
	v_cmp_lt_i32_e32 vcc, v9, v11
	v_lshlrev_b32_e32 v10, 4, v10
	s_waitcnt vmcnt(17)
	v_and_b32_e32 v17, 0x3f0, v10
	v_cndmask_b32_e32 v9, v221, v9, vcc
	v_lshlrev_b32_e32 v14, 2, v9
	v_xor_b32_e32 v9, 4, v221
	v_cmp_lt_i32_e32 vcc, v9, v11
	v_readlane_b32 s41, v250, 25
	v_readlane_b32 s42, v250, 26
	v_cndmask_b32_e32 v9, v221, v9, vcc
	v_lshlrev_b32_e32 v15, 2, v9
	v_xor_b32_e32 v9, 8, v221
	v_cmp_lt_i32_e32 vcc, v9, v11
	v_readlane_b32 s43, v250, 27
	v_readlane_b32 s44, v250, 28
	v_cndmask_b32_e32 v9, v221, v9, vcc
	v_lshlrev_b32_e32 v16, 2, v9
	v_ashrrev_i32_e32 v9, 31, v8
	v_lshl_add_u64 v[18:19], s[4:5], 0, v[8:9]
	s_movk_i32 s4, 0x1800
	v_mad_u64_u32 v[8:9], s[8:9], v18, s4, 0
	v_mad_i32_i24 v9, v19, s4, v9
	v_readlane_b32 s4, v246, 10
	v_or_b32_e32 v8, v8, v17
	v_readlane_b32 s5, v246, 11
	v_lshlrev_b64 v[10:11], 11, v[18:19]
	v_or_b32_e32 v10, v10, v17
	v_lshl_add_u64 v[8:9], s[4:5], 0, v[8:9]
	v_readlane_b32 s4, v250, 10
	v_readlane_b32 s5, v250, 11
	s_mov_b64 s[8:9], 0
	v_readlane_b32 s45, v250, 29
	v_lshl_add_u64 v[10:11], s[4:5], 0, v[10:11]
	v_readlane_b32 s4, v248, 58
	v_readlane_b32 s46, v250, 30
	v_readlane_b32 s47, v250, 31
	v_readlane_b32 s48, v250, 32
	v_readlane_b32 s49, v250, 33
	v_readlane_b32 s50, v250, 34
	v_readlane_b32 s51, v250, 35
	v_readlane_b32 s12, v250, 2
	s_nop 3
	s_cmp_lg_u32 s12, 0
	s_cbranch_scc0 .LBB0_682
	v_mov_b32_e32 v50, v10
	v_mov_b32_e32 v51, v11
	global_load_dwordx4 v[52:55], v[10:11], off
	global_load_dwordx4 v[56:59], v[8:9], off
	v_lshl_add_u64 v[10:11], v[10:11], 0, s[18:19]
	v_lshl_add_u64 v[8:9], v[8:9], 0, s[16:17]
	global_load_dwordx4 v[60:63], v[10:11], off
	global_load_dwordx4 v[64:67], v[8:9], off
	v_lshl_add_u64 v[10:11], v[10:11], 0, s[18:19]
	v_lshl_add_u64 v[8:9], v[8:9], 0, s[16:17]
	global_load_dwordx4 v[68:71], v[10:11], off
	global_load_dwordx4 v[72:75], v[8:9], off
	v_lshl_add_u64 v[10:11], v[10:11], 0, s[18:19]
	v_lshl_add_u64 v[8:9], v[8:9], 0, s[16:17]
	global_load_dwordx4 v[76:79], v[10:11], off
	global_load_dwordx4 v[80:83], v[8:9], off
	v_lshl_add_u64 v[10:11], v[10:11], 0, s[18:19]
	v_lshl_add_u64 v[8:9], v[8:9], 0, s[16:17]
	global_load_dwordx4 v[84:87], v[10:11], off
	global_load_dwordx4 v[88:91], v[8:9], off
	v_lshl_add_u64 v[10:11], v[10:11], 0, s[18:19]
	v_lshl_add_u64 v[8:9], v[8:9], 0, s[16:17]
	global_load_dwordx4 v[92:95], v[10:11], off
	global_load_dwordx4 v[96:99], v[8:9], off
	v_lshl_add_u64 v[10:11], v[10:11], 0, s[18:19]
	v_lshl_add_u64 v[8:9], v[8:9], 0, s[16:17]
	global_load_dwordx4 v[100:103], v[10:11], off
	global_load_dwordx4 v[104:107], v[8:9], off
	v_lshl_add_u64 v[10:11], v[10:11], 0, s[18:19]
	v_lshl_add_u64 v[8:9], v[8:9], 0, s[16:17]
	global_load_dwordx4 v[108:111], v[10:11], off
	global_load_dwordx4 v[112:115], v[8:9], off
	v_lshl_add_u64 v[10:11], v[10:11], 0, s[18:19]
	v_lshl_add_u64 v[8:9], v[8:9], 0, s[16:17]
	global_load_dwordx4 v[116:119], v[10:11], off
	global_load_dwordx4 v[120:123], v[8:9], off
	v_lshl_add_u64 v[10:11], v[10:11], 0, s[18:19]
	v_lshl_add_u64 v[8:9], v[8:9], 0, s[16:17]
	global_load_dwordx4 v[124:127], v[10:11], off
	global_load_dwordx4 v[128:131], v[8:9], off
	v_lshl_add_u64 v[10:11], v[10:11], 0, s[18:19]
	v_lshl_add_u64 v[8:9], v[8:9], 0, s[16:17]
	global_load_dwordx4 v[132:135], v[10:11], off
	global_load_dwordx4 v[136:139], v[8:9], off
	v_lshl_add_u64 v[10:11], v[10:11], 0, s[18:19]
	v_lshl_add_u64 v[8:9], v[8:9], 0, s[16:17]
	global_load_dwordx4 v[140:143], v[10:11], off
	global_load_dwordx4 v[144:147], v[8:9], off
	v_lshl_add_u64 v[10:11], v[10:11], 0, s[18:19]
	v_lshl_add_u64 v[8:9], v[8:9], 0, s[16:17]
	global_load_dwordx4 v[148:151], v[10:11], off
	global_load_dwordx4 v[152:155], v[8:9], off
	v_lshl_add_u64 v[10:11], v[10:11], 0, s[18:19]
	v_lshl_add_u64 v[8:9], v[8:9], 0, s[16:17]
	global_load_dwordx4 v[156:159], v[10:11], off
	global_load_dwordx4 v[160:163], v[8:9], off
	v_lshl_add_u64 v[10:11], v[10:11], 0, s[18:19]
	v_lshl_add_u64 v[8:9], v[8:9], 0, s[16:17]
	global_load_dwordx4 v[180:183], v[10:11], off
	global_load_dwordx4 v[184:187], v[8:9], off
	v_lshl_add_u64 v[10:11], v[10:11], 0, s[18:19]
	v_lshl_add_u64 v[8:9], v[8:9], 0, s[16:17]
	global_load_dwordx4 v[188:191], v[10:11], off
	global_load_dwordx4 v[192:195], v[8:9], off
	s_waitcnt vmcnt(30)
	v_lshlrev_b32_e32 v26, 16, v52
	v_and_b32_e32 v27, 0xffff0000, v52
	v_lshlrev_b32_e32 v28, 16, v53
	v_and_b32_e32 v29, 0xffff0000, v53
	v_lshlrev_b32_e32 v30, 16, v54
	v_and_b32_e32 v31, 0xffff0000, v54
	v_lshlrev_b32_e32 v32, 16, v55
	v_and_b32_e32 v33, 0xffff0000, v55
	v_lshlrev_b32_e32 v34, 16, v56
	v_and_b32_e32 v35, 0xffff0000, v56
	v_lshlrev_b32_e32 v36, 16, v57
	v_and_b32_e32 v37, 0xffff0000, v57
	v_lshlrev_b32_e32 v38, 16, v58
	v_and_b32_e32 v39, 0xffff0000, v58
	v_lshlrev_b32_e32 v40, 16, v59
	v_and_b32_e32 v41, 0xffff0000, v59
	v_pk_mul_f32 v[42:43], v[26:27], v[26:27]
	v_add_f32_e32 v44, v42, v43
	v_pk_mul_f32 v[42:43], v[28:29], v[28:29]
	v_add_f32_e32 v44, v42, v44
	v_add_f32_e32 v44, v43, v44
	v_pk_mul_f32 v[42:43], v[30:31], v[30:31]
	v_add_f32_e32 v44, v42, v44
	v_add_f32_e32 v44, v43, v44
	v_pk_mul_f32 v[42:43], v[32:33], v[32:33]
	v_add_f32_e32 v44, v42, v44
	v_add_f32_e32 v44, v43, v44
	v_mul_f32_e32 v18, 0xbfb8aa3b, v34
	v_mul_f32_e32 v19, 0xbfb8aa3b, v35
	v_mul_f32_e32 v20, 0xbfb8aa3b, v36
	v_mul_f32_e32 v21, 0xbfb8aa3b, v37
	v_mul_f32_e32 v22, 0xbfb8aa3b, v38
	v_mul_f32_e32 v23, 0xbfb8aa3b, v39
	v_mul_f32_e32 v24, 0xbfb8aa3b, v40
	v_mul_f32_e32 v25, 0xbfb8aa3b, v41
	v_add_f32_dpp v45, v44, v44 quad_perm:[1,0,3,2] row_mask:0xf bank_mask:0xf
	v_exp_f32_e32 v18, v18
	v_exp_f32_e32 v19, v19
	v_exp_f32_e32 v20, v20
	v_exp_f32_e32 v21, v21
	v_add_f32_dpp v44, v45, v45 quad_perm:[2,3,0,1] row_mask:0xf bank_mask:0xf
	v_exp_f32_e32 v22, v22
	v_exp_f32_e32 v23, v23
	v_exp_f32_e32 v24, v24
	v_exp_f32_e32 v25, v25
	v_add_f32_dpp v45, v44, v44 row_half_mirror row_mask:0xf bank_mask:0xf
	v_add_f32_e32 v18, 1.0, v18
	v_add_f32_e32 v19, 1.0, v19
	v_add_f32_e32 v20, 1.0, v20
	v_add_f32_e32 v21, 1.0, v21
	v_add_f32_dpp v44, v45, v45 row_mirror row_mask:0xf bank_mask:0xf
	v_add_f32_e32 v22, 1.0, v22
	v_add_f32_e32 v23, 1.0, v23
	v_add_f32_e32 v24, 1.0, v24
	v_add_f32_e32 v25, 1.0, v25
	v_fmamk_f32 v44, v44, 0x3c000000, v218
	v_rcp_f32_e32 v18, v18
	v_rcp_f32_e32 v19, v19
	v_rcp_f32_e32 v20, v20
	v_rcp_f32_e32 v21, v21
	v_rcp_f32_e32 v22, v22
	v_rcp_f32_e32 v23, v23
	v_mul_f32_e32 v45, 0x4b800000, v44
	v_cmp_gt_f32_e32 vcc, s11, v44
	v_rcp_f32_e32 v24, v24
	v_rcp_f32_e32 v25, v25
	v_cndmask_b32_e32 v44, v44, v45, vcc
	v_rsq_f32_e32 v44, v44
	v_pk_mul_f32 v[18:19], v[18:19], v[34:35]
	v_mul_f32_e32 v45, 0x45800000, v44
	v_cndmask_b32_e32 v46, v44, v45, vcc
	v_pk_mul_f32 v[20:21], v[20:21], v[36:37]
	v_pk_mul_f32 v[22:23], v[22:23], v[38:39]
	v_pk_mul_f32 v[24:25], v[24:25], v[40:41]
	v_pk_mul_f32 v[26:27], v[46:47], v[26:27] op_sel_hi:[0,1]
	v_pk_mul_f32 v[28:29], v[46:47], v[28:29] op_sel_hi:[0,1]
	v_pk_mul_f32 v[30:31], v[46:47], v[30:31] op_sel_hi:[0,1]
	v_pk_mul_f32 v[32:33], v[46:47], v[32:33] op_sel_hi:[0,1]
	v_pk_mul_f32 v[26:27], v[0:1], v[26:27]
	v_pk_mul_f32 v[28:29], v[2:3], v[28:29]
	v_pk_mul_f32 v[30:31], v[4:5], v[30:31]
	v_pk_mul_f32 v[32:33], v[6:7], v[32:33]
	v_pk_mul_f32 v[26:27], v[18:19], v[26:27]
	v_pk_mul_f32 v[28:29], v[20:21], v[28:29]
	v_pk_mul_f32 v[30:31], v[22:23], v[30:31]
	v_pk_mul_f32 v[32:33], v[24:25], v[32:33]
	v_cvt_pk_bf16_f32 v52, v26, v27
	v_cvt_pk_bf16_f32 v53, v28, v29
	v_cvt_pk_bf16_f32 v54, v30, v31
	v_cvt_pk_bf16_f32 v55, v32, v33
	global_store_dwordx4 v[50:51], v[52:55], off
	v_lshl_add_u64 v[50:51], v[50:51], 0, s[18:19]
	s_waitcnt vmcnt(29)
	v_lshlrev_b32_e32 v26, 16, v60
	v_and_b32_e32 v27, 0xffff0000, v60
	v_lshlrev_b32_e32 v28, 16, v61
	v_and_b32_e32 v29, 0xffff0000, v61
	v_lshlrev_b32_e32 v30, 16, v62
	v_and_b32_e32 v31, 0xffff0000, v62
	v_lshlrev_b32_e32 v32, 16, v63
	v_and_b32_e32 v33, 0xffff0000, v63
	v_lshlrev_b32_e32 v34, 16, v64
	v_and_b32_e32 v35, 0xffff0000, v64
	v_lshlrev_b32_e32 v36, 16, v65
	v_and_b32_e32 v37, 0xffff0000, v65
	v_lshlrev_b32_e32 v38, 16, v66
	v_and_b32_e32 v39, 0xffff0000, v66
	v_lshlrev_b32_e32 v40, 16, v67
	v_and_b32_e32 v41, 0xffff0000, v67
	v_pk_mul_f32 v[42:43], v[26:27], v[26:27]
	v_add_f32_e32 v44, v42, v43
	v_pk_mul_f32 v[42:43], v[28:29], v[28:29]
	v_add_f32_e32 v44, v42, v44
	v_add_f32_e32 v44, v43, v44
	v_pk_mul_f32 v[42:43], v[30:31], v[30:31]
	v_add_f32_e32 v44, v42, v44
	v_add_f32_e32 v44, v43, v44
	v_pk_mul_f32 v[42:43], v[32:33], v[32:33]
	v_add_f32_e32 v44, v42, v44
	v_add_f32_e32 v44, v43, v44
	v_mul_f32_e32 v18, 0xbfb8aa3b, v34
	v_mul_f32_e32 v19, 0xbfb8aa3b, v35
	v_mul_f32_e32 v20, 0xbfb8aa3b, v36
	v_mul_f32_e32 v21, 0xbfb8aa3b, v37
	v_mul_f32_e32 v22, 0xbfb8aa3b, v38
	v_mul_f32_e32 v23, 0xbfb8aa3b, v39
	v_mul_f32_e32 v24, 0xbfb8aa3b, v40
	v_mul_f32_e32 v25, 0xbfb8aa3b, v41
	v_add_f32_dpp v45, v44, v44 quad_perm:[1,0,3,2] row_mask:0xf bank_mask:0xf
	v_exp_f32_e32 v18, v18
	v_exp_f32_e32 v19, v19
	v_exp_f32_e32 v20, v20
	v_exp_f32_e32 v21, v21
	v_add_f32_dpp v44, v45, v45 quad_perm:[2,3,0,1] row_mask:0xf bank_mask:0xf
	v_exp_f32_e32 v22, v22
	v_exp_f32_e32 v23, v23
	v_exp_f32_e32 v24, v24
	v_exp_f32_e32 v25, v25
	v_add_f32_dpp v45, v44, v44 row_half_mirror row_mask:0xf bank_mask:0xf
	v_add_f32_e32 v18, 1.0, v18
	v_add_f32_e32 v19, 1.0, v19
	v_add_f32_e32 v20, 1.0, v20
	v_add_f32_e32 v21, 1.0, v21
	v_add_f32_dpp v44, v45, v45 row_mirror row_mask:0xf bank_mask:0xf
	v_add_f32_e32 v22, 1.0, v22
	v_add_f32_e32 v23, 1.0, v23
	v_add_f32_e32 v24, 1.0, v24
	v_add_f32_e32 v25, 1.0, v25
	v_fmamk_f32 v44, v44, 0x3c000000, v218
	v_rcp_f32_e32 v18, v18
	v_rcp_f32_e32 v19, v19
	v_rcp_f32_e32 v20, v20
	v_rcp_f32_e32 v21, v21
	v_rcp_f32_e32 v22, v22
	v_rcp_f32_e32 v23, v23
	v_mul_f32_e32 v45, 0x4b800000, v44
	v_cmp_gt_f32_e32 vcc, s11, v44
	v_rcp_f32_e32 v24, v24
	v_rcp_f32_e32 v25, v25
	v_cndmask_b32_e32 v44, v44, v45, vcc
	v_rsq_f32_e32 v44, v44
	v_pk_mul_f32 v[18:19], v[18:19], v[34:35]
	v_mul_f32_e32 v45, 0x45800000, v44
	v_cndmask_b32_e32 v46, v44, v45, vcc
	v_pk_mul_f32 v[20:21], v[20:21], v[36:37]
	v_pk_mul_f32 v[22:23], v[22:23], v[38:39]
	v_pk_mul_f32 v[24:25], v[24:25], v[40:41]
	v_pk_mul_f32 v[26:27], v[46:47], v[26:27] op_sel_hi:[0,1]
	v_pk_mul_f32 v[28:29], v[46:47], v[28:29] op_sel_hi:[0,1]
	v_pk_mul_f32 v[30:31], v[46:47], v[30:31] op_sel_hi:[0,1]
	v_pk_mul_f32 v[32:33], v[46:47], v[32:33] op_sel_hi:[0,1]
	v_pk_mul_f32 v[26:27], v[0:1], v[26:27]
	v_pk_mul_f32 v[28:29], v[2:3], v[28:29]
	v_pk_mul_f32 v[30:31], v[4:5], v[30:31]
	v_pk_mul_f32 v[32:33], v[6:7], v[32:33]
	v_pk_mul_f32 v[26:27], v[18:19], v[26:27]
	v_pk_mul_f32 v[28:29], v[20:21], v[28:29]
	v_pk_mul_f32 v[30:31], v[22:23], v[30:31]
	v_pk_mul_f32 v[32:33], v[24:25], v[32:33]
	v_cvt_pk_bf16_f32 v60, v26, v27
	v_cvt_pk_bf16_f32 v61, v28, v29
	v_cvt_pk_bf16_f32 v62, v30, v31
	v_cvt_pk_bf16_f32 v63, v32, v33
	global_store_dwordx4 v[50:51], v[60:63], off
	v_lshl_add_u64 v[50:51], v[50:51], 0, s[18:19]
	s_waitcnt vmcnt(28)
	v_lshlrev_b32_e32 v26, 16, v68
	v_and_b32_e32 v27, 0xffff0000, v68
	v_lshlrev_b32_e32 v28, 16, v69
	v_and_b32_e32 v29, 0xffff0000, v69
	v_lshlrev_b32_e32 v30, 16, v70
	v_and_b32_e32 v31, 0xffff0000, v70
	v_lshlrev_b32_e32 v32, 16, v71
	v_and_b32_e32 v33, 0xffff0000, v71
	v_lshlrev_b32_e32 v34, 16, v72
	v_and_b32_e32 v35, 0xffff0000, v72
	v_lshlrev_b32_e32 v36, 16, v73
	v_and_b32_e32 v37, 0xffff0000, v73
	v_lshlrev_b32_e32 v38, 16, v74
	v_and_b32_e32 v39, 0xffff0000, v74
	v_lshlrev_b32_e32 v40, 16, v75
	v_and_b32_e32 v41, 0xffff0000, v75
	v_pk_mul_f32 v[42:43], v[26:27], v[26:27]
	v_add_f32_e32 v44, v42, v43
	v_pk_mul_f32 v[42:43], v[28:29], v[28:29]
	v_add_f32_e32 v44, v42, v44
	v_add_f32_e32 v44, v43, v44
	v_pk_mul_f32 v[42:43], v[30:31], v[30:31]
	v_add_f32_e32 v44, v42, v44
	v_add_f32_e32 v44, v43, v44
	v_pk_mul_f32 v[42:43], v[32:33], v[32:33]
	v_add_f32_e32 v44, v42, v44
	v_add_f32_e32 v44, v43, v44
	v_mul_f32_e32 v18, 0xbfb8aa3b, v34
	v_mul_f32_e32 v19, 0xbfb8aa3b, v35
	v_mul_f32_e32 v20, 0xbfb8aa3b, v36
	v_mul_f32_e32 v21, 0xbfb8aa3b, v37
	v_mul_f32_e32 v22, 0xbfb8aa3b, v38
	v_mul_f32_e32 v23, 0xbfb8aa3b, v39
	v_mul_f32_e32 v24, 0xbfb8aa3b, v40
	v_mul_f32_e32 v25, 0xbfb8aa3b, v41
	v_add_f32_dpp v45, v44, v44 quad_perm:[1,0,3,2] row_mask:0xf bank_mask:0xf
	v_exp_f32_e32 v18, v18
	v_exp_f32_e32 v19, v19
	v_exp_f32_e32 v20, v20
	v_exp_f32_e32 v21, v21
	v_add_f32_dpp v44, v45, v45 quad_perm:[2,3,0,1] row_mask:0xf bank_mask:0xf
	v_exp_f32_e32 v22, v22
	v_exp_f32_e32 v23, v23
	v_exp_f32_e32 v24, v24
	v_exp_f32_e32 v25, v25
	v_add_f32_dpp v45, v44, v44 row_half_mirror row_mask:0xf bank_mask:0xf
	v_add_f32_e32 v18, 1.0, v18
	v_add_f32_e32 v19, 1.0, v19
	v_add_f32_e32 v20, 1.0, v20
	v_add_f32_e32 v21, 1.0, v21
	v_add_f32_dpp v44, v45, v45 row_mirror row_mask:0xf bank_mask:0xf
	v_add_f32_e32 v22, 1.0, v22
	v_add_f32_e32 v23, 1.0, v23
	v_add_f32_e32 v24, 1.0, v24
	v_add_f32_e32 v25, 1.0, v25
	v_fmamk_f32 v44, v44, 0x3c000000, v218
	v_rcp_f32_e32 v18, v18
	v_rcp_f32_e32 v19, v19
	v_rcp_f32_e32 v20, v20
	v_rcp_f32_e32 v21, v21
	v_rcp_f32_e32 v22, v22
	v_rcp_f32_e32 v23, v23
	v_mul_f32_e32 v45, 0x4b800000, v44
	v_cmp_gt_f32_e32 vcc, s11, v44
	v_rcp_f32_e32 v24, v24
	v_rcp_f32_e32 v25, v25
	v_cndmask_b32_e32 v44, v44, v45, vcc
	v_rsq_f32_e32 v44, v44
	v_pk_mul_f32 v[18:19], v[18:19], v[34:35]
	v_mul_f32_e32 v45, 0x45800000, v44
	v_cndmask_b32_e32 v46, v44, v45, vcc
	v_pk_mul_f32 v[20:21], v[20:21], v[36:37]
	v_pk_mul_f32 v[22:23], v[22:23], v[38:39]
	v_pk_mul_f32 v[24:25], v[24:25], v[40:41]
	v_pk_mul_f32 v[26:27], v[46:47], v[26:27] op_sel_hi:[0,1]
	v_pk_mul_f32 v[28:29], v[46:47], v[28:29] op_sel_hi:[0,1]
	v_pk_mul_f32 v[30:31], v[46:47], v[30:31] op_sel_hi:[0,1]
	v_pk_mul_f32 v[32:33], v[46:47], v[32:33] op_sel_hi:[0,1]
	v_pk_mul_f32 v[26:27], v[0:1], v[26:27]
	v_pk_mul_f32 v[28:29], v[2:3], v[28:29]
	v_pk_mul_f32 v[30:31], v[4:5], v[30:31]
	v_pk_mul_f32 v[32:33], v[6:7], v[32:33]
	v_pk_mul_f32 v[26:27], v[18:19], v[26:27]
	v_pk_mul_f32 v[28:29], v[20:21], v[28:29]
	v_pk_mul_f32 v[30:31], v[22:23], v[30:31]
	v_pk_mul_f32 v[32:33], v[24:25], v[32:33]
	v_cvt_pk_bf16_f32 v68, v26, v27
	v_cvt_pk_bf16_f32 v69, v28, v29
	v_cvt_pk_bf16_f32 v70, v30, v31
	v_cvt_pk_bf16_f32 v71, v32, v33
	global_store_dwordx4 v[50:51], v[68:71], off
	v_lshl_add_u64 v[50:51], v[50:51], 0, s[18:19]
	s_waitcnt vmcnt(27)
	v_lshlrev_b32_e32 v26, 16, v76
	v_and_b32_e32 v27, 0xffff0000, v76
	v_lshlrev_b32_e32 v28, 16, v77
	v_and_b32_e32 v29, 0xffff0000, v77
	v_lshlrev_b32_e32 v30, 16, v78
	v_and_b32_e32 v31, 0xffff0000, v78
	v_lshlrev_b32_e32 v32, 16, v79
	v_and_b32_e32 v33, 0xffff0000, v79
	v_lshlrev_b32_e32 v34, 16, v80
	v_and_b32_e32 v35, 0xffff0000, v80
	v_lshlrev_b32_e32 v36, 16, v81
	v_and_b32_e32 v37, 0xffff0000, v81
	v_lshlrev_b32_e32 v38, 16, v82
	v_and_b32_e32 v39, 0xffff0000, v82
	v_lshlrev_b32_e32 v40, 16, v83
	v_and_b32_e32 v41, 0xffff0000, v83
	v_pk_mul_f32 v[42:43], v[26:27], v[26:27]
	v_add_f32_e32 v44, v42, v43
	v_pk_mul_f32 v[42:43], v[28:29], v[28:29]
	v_add_f32_e32 v44, v42, v44
	v_add_f32_e32 v44, v43, v44
	v_pk_mul_f32 v[42:43], v[30:31], v[30:31]
	v_add_f32_e32 v44, v42, v44
	v_add_f32_e32 v44, v43, v44
	v_pk_mul_f32 v[42:43], v[32:33], v[32:33]
	v_add_f32_e32 v44, v42, v44
	v_add_f32_e32 v44, v43, v44
	v_mul_f32_e32 v18, 0xbfb8aa3b, v34
	v_mul_f32_e32 v19, 0xbfb8aa3b, v35
	v_mul_f32_e32 v20, 0xbfb8aa3b, v36
	v_mul_f32_e32 v21, 0xbfb8aa3b, v37
	v_mul_f32_e32 v22, 0xbfb8aa3b, v38
	v_mul_f32_e32 v23, 0xbfb8aa3b, v39
	v_mul_f32_e32 v24, 0xbfb8aa3b, v40
	v_mul_f32_e32 v25, 0xbfb8aa3b, v41
	v_add_f32_dpp v45, v44, v44 quad_perm:[1,0,3,2] row_mask:0xf bank_mask:0xf
	v_exp_f32_e32 v18, v18
	v_exp_f32_e32 v19, v19
	v_exp_f32_e32 v20, v20
	v_exp_f32_e32 v21, v21
	v_add_f32_dpp v44, v45, v45 quad_perm:[2,3,0,1] row_mask:0xf bank_mask:0xf
	v_exp_f32_e32 v22, v22
	v_exp_f32_e32 v23, v23
	v_exp_f32_e32 v24, v24
	v_exp_f32_e32 v25, v25
	v_add_f32_dpp v45, v44, v44 row_half_mirror row_mask:0xf bank_mask:0xf
	v_add_f32_e32 v18, 1.0, v18
	v_add_f32_e32 v19, 1.0, v19
	v_add_f32_e32 v20, 1.0, v20
	v_add_f32_e32 v21, 1.0, v21
	v_add_f32_dpp v44, v45, v45 row_mirror row_mask:0xf bank_mask:0xf
	v_add_f32_e32 v22, 1.0, v22
	v_add_f32_e32 v23, 1.0, v23
	v_add_f32_e32 v24, 1.0, v24
	v_add_f32_e32 v25, 1.0, v25
	v_fmamk_f32 v44, v44, 0x3c000000, v218
	v_rcp_f32_e32 v18, v18
	v_rcp_f32_e32 v19, v19
	v_rcp_f32_e32 v20, v20
	v_rcp_f32_e32 v21, v21
	v_rcp_f32_e32 v22, v22
	v_rcp_f32_e32 v23, v23
	v_mul_f32_e32 v45, 0x4b800000, v44
	v_cmp_gt_f32_e32 vcc, s11, v44
	v_rcp_f32_e32 v24, v24
	v_rcp_f32_e32 v25, v25
	v_cndmask_b32_e32 v44, v44, v45, vcc
	v_rsq_f32_e32 v44, v44
	v_pk_mul_f32 v[18:19], v[18:19], v[34:35]
	v_mul_f32_e32 v45, 0x45800000, v44
	v_cndmask_b32_e32 v46, v44, v45, vcc
	v_pk_mul_f32 v[20:21], v[20:21], v[36:37]
	v_pk_mul_f32 v[22:23], v[22:23], v[38:39]
	v_pk_mul_f32 v[24:25], v[24:25], v[40:41]
	v_pk_mul_f32 v[26:27], v[46:47], v[26:27] op_sel_hi:[0,1]
	v_pk_mul_f32 v[28:29], v[46:47], v[28:29] op_sel_hi:[0,1]
	v_pk_mul_f32 v[30:31], v[46:47], v[30:31] op_sel_hi:[0,1]
	v_pk_mul_f32 v[32:33], v[46:47], v[32:33] op_sel_hi:[0,1]
	v_pk_mul_f32 v[26:27], v[0:1], v[26:27]
	v_pk_mul_f32 v[28:29], v[2:3], v[28:29]
	v_pk_mul_f32 v[30:31], v[4:5], v[30:31]
	v_pk_mul_f32 v[32:33], v[6:7], v[32:33]
	v_pk_mul_f32 v[26:27], v[18:19], v[26:27]
	v_pk_mul_f32 v[28:29], v[20:21], v[28:29]
	v_pk_mul_f32 v[30:31], v[22:23], v[30:31]
	v_pk_mul_f32 v[32:33], v[24:25], v[32:33]
	v_cvt_pk_bf16_f32 v76, v26, v27
	v_cvt_pk_bf16_f32 v77, v28, v29
	v_cvt_pk_bf16_f32 v78, v30, v31
	v_cvt_pk_bf16_f32 v79, v32, v33
	global_store_dwordx4 v[50:51], v[76:79], off
	v_lshl_add_u64 v[50:51], v[50:51], 0, s[18:19]
	s_waitcnt vmcnt(26)
	v_lshlrev_b32_e32 v26, 16, v84
	v_and_b32_e32 v27, 0xffff0000, v84
	v_lshlrev_b32_e32 v28, 16, v85
	v_and_b32_e32 v29, 0xffff0000, v85
	v_lshlrev_b32_e32 v30, 16, v86
	v_and_b32_e32 v31, 0xffff0000, v86
	v_lshlrev_b32_e32 v32, 16, v87
	v_and_b32_e32 v33, 0xffff0000, v87
	v_lshlrev_b32_e32 v34, 16, v88
	v_and_b32_e32 v35, 0xffff0000, v88
	v_lshlrev_b32_e32 v36, 16, v89
	v_and_b32_e32 v37, 0xffff0000, v89
	v_lshlrev_b32_e32 v38, 16, v90
	v_and_b32_e32 v39, 0xffff0000, v90
	v_lshlrev_b32_e32 v40, 16, v91
	v_and_b32_e32 v41, 0xffff0000, v91
	v_pk_mul_f32 v[42:43], v[26:27], v[26:27]
	v_add_f32_e32 v44, v42, v43
	v_pk_mul_f32 v[42:43], v[28:29], v[28:29]
	v_add_f32_e32 v44, v42, v44
	v_add_f32_e32 v44, v43, v44
	v_pk_mul_f32 v[42:43], v[30:31], v[30:31]
	v_add_f32_e32 v44, v42, v44
	v_add_f32_e32 v44, v43, v44
	v_pk_mul_f32 v[42:43], v[32:33], v[32:33]
	v_add_f32_e32 v44, v42, v44
	v_add_f32_e32 v44, v43, v44
	v_mul_f32_e32 v18, 0xbfb8aa3b, v34
	v_mul_f32_e32 v19, 0xbfb8aa3b, v35
	v_mul_f32_e32 v20, 0xbfb8aa3b, v36
	v_mul_f32_e32 v21, 0xbfb8aa3b, v37
	v_mul_f32_e32 v22, 0xbfb8aa3b, v38
	v_mul_f32_e32 v23, 0xbfb8aa3b, v39
	v_mul_f32_e32 v24, 0xbfb8aa3b, v40
	v_mul_f32_e32 v25, 0xbfb8aa3b, v41
	v_add_f32_dpp v45, v44, v44 quad_perm:[1,0,3,2] row_mask:0xf bank_mask:0xf
	v_exp_f32_e32 v18, v18
	v_exp_f32_e32 v19, v19
	v_exp_f32_e32 v20, v20
	v_exp_f32_e32 v21, v21
	v_add_f32_dpp v44, v45, v45 quad_perm:[2,3,0,1] row_mask:0xf bank_mask:0xf
	v_exp_f32_e32 v22, v22
	v_exp_f32_e32 v23, v23
	v_exp_f32_e32 v24, v24
	v_exp_f32_e32 v25, v25
	v_add_f32_dpp v45, v44, v44 row_half_mirror row_mask:0xf bank_mask:0xf
	v_add_f32_e32 v18, 1.0, v18
	v_add_f32_e32 v19, 1.0, v19
	v_add_f32_e32 v20, 1.0, v20
	v_add_f32_e32 v21, 1.0, v21
	v_add_f32_dpp v44, v45, v45 row_mirror row_mask:0xf bank_mask:0xf
	v_add_f32_e32 v22, 1.0, v22
	v_add_f32_e32 v23, 1.0, v23
	v_add_f32_e32 v24, 1.0, v24
	v_add_f32_e32 v25, 1.0, v25
	v_fmamk_f32 v44, v44, 0x3c000000, v218
	v_rcp_f32_e32 v18, v18
	v_rcp_f32_e32 v19, v19
	v_rcp_f32_e32 v20, v20
	v_rcp_f32_e32 v21, v21
	v_rcp_f32_e32 v22, v22
	v_rcp_f32_e32 v23, v23
	v_mul_f32_e32 v45, 0x4b800000, v44
	v_cmp_gt_f32_e32 vcc, s11, v44
	v_rcp_f32_e32 v24, v24
	v_rcp_f32_e32 v25, v25
	v_cndmask_b32_e32 v44, v44, v45, vcc
	v_rsq_f32_e32 v44, v44
	v_pk_mul_f32 v[18:19], v[18:19], v[34:35]
	v_mul_f32_e32 v45, 0x45800000, v44
	v_cndmask_b32_e32 v46, v44, v45, vcc
	v_pk_mul_f32 v[20:21], v[20:21], v[36:37]
	v_pk_mul_f32 v[22:23], v[22:23], v[38:39]
	v_pk_mul_f32 v[24:25], v[24:25], v[40:41]
	v_pk_mul_f32 v[26:27], v[46:47], v[26:27] op_sel_hi:[0,1]
	v_pk_mul_f32 v[28:29], v[46:47], v[28:29] op_sel_hi:[0,1]
	v_pk_mul_f32 v[30:31], v[46:47], v[30:31] op_sel_hi:[0,1]
	v_pk_mul_f32 v[32:33], v[46:47], v[32:33] op_sel_hi:[0,1]
	v_pk_mul_f32 v[26:27], v[0:1], v[26:27]
	v_pk_mul_f32 v[28:29], v[2:3], v[28:29]
	v_pk_mul_f32 v[30:31], v[4:5], v[30:31]
	v_pk_mul_f32 v[32:33], v[6:7], v[32:33]
	v_pk_mul_f32 v[26:27], v[18:19], v[26:27]
	v_pk_mul_f32 v[28:29], v[20:21], v[28:29]
	v_pk_mul_f32 v[30:31], v[22:23], v[30:31]
	v_pk_mul_f32 v[32:33], v[24:25], v[32:33]
	v_cvt_pk_bf16_f32 v84, v26, v27
	v_cvt_pk_bf16_f32 v85, v28, v29
	v_cvt_pk_bf16_f32 v86, v30, v31
	v_cvt_pk_bf16_f32 v87, v32, v33
	global_store_dwordx4 v[50:51], v[84:87], off
	v_lshl_add_u64 v[50:51], v[50:51], 0, s[18:19]
	s_waitcnt vmcnt(25)
	v_lshlrev_b32_e32 v26, 16, v92
	v_and_b32_e32 v27, 0xffff0000, v92
	v_lshlrev_b32_e32 v28, 16, v93
	v_and_b32_e32 v29, 0xffff0000, v93
	v_lshlrev_b32_e32 v30, 16, v94
	v_and_b32_e32 v31, 0xffff0000, v94
	v_lshlrev_b32_e32 v32, 16, v95
	v_and_b32_e32 v33, 0xffff0000, v95
	v_lshlrev_b32_e32 v34, 16, v96
	v_and_b32_e32 v35, 0xffff0000, v96
	v_lshlrev_b32_e32 v36, 16, v97
	v_and_b32_e32 v37, 0xffff0000, v97
	v_lshlrev_b32_e32 v38, 16, v98
	v_and_b32_e32 v39, 0xffff0000, v98
	v_lshlrev_b32_e32 v40, 16, v99
	v_and_b32_e32 v41, 0xffff0000, v99
	v_pk_mul_f32 v[42:43], v[26:27], v[26:27]
	v_add_f32_e32 v44, v42, v43
	v_pk_mul_f32 v[42:43], v[28:29], v[28:29]
	v_add_f32_e32 v44, v42, v44
	v_add_f32_e32 v44, v43, v44
	v_pk_mul_f32 v[42:43], v[30:31], v[30:31]
	v_add_f32_e32 v44, v42, v44
	v_add_f32_e32 v44, v43, v44
	v_pk_mul_f32 v[42:43], v[32:33], v[32:33]
	v_add_f32_e32 v44, v42, v44
	v_add_f32_e32 v44, v43, v44
	v_mul_f32_e32 v18, 0xbfb8aa3b, v34
	v_mul_f32_e32 v19, 0xbfb8aa3b, v35
	v_mul_f32_e32 v20, 0xbfb8aa3b, v36
	v_mul_f32_e32 v21, 0xbfb8aa3b, v37
	v_mul_f32_e32 v22, 0xbfb8aa3b, v38
	v_mul_f32_e32 v23, 0xbfb8aa3b, v39
	v_mul_f32_e32 v24, 0xbfb8aa3b, v40
	v_mul_f32_e32 v25, 0xbfb8aa3b, v41
	v_add_f32_dpp v45, v44, v44 quad_perm:[1,0,3,2] row_mask:0xf bank_mask:0xf
	v_exp_f32_e32 v18, v18
	v_exp_f32_e32 v19, v19
	v_exp_f32_e32 v20, v20
	v_exp_f32_e32 v21, v21
	v_add_f32_dpp v44, v45, v45 quad_perm:[2,3,0,1] row_mask:0xf bank_mask:0xf
	v_exp_f32_e32 v22, v22
	v_exp_f32_e32 v23, v23
	v_exp_f32_e32 v24, v24
	v_exp_f32_e32 v25, v25
	v_add_f32_dpp v45, v44, v44 row_half_mirror row_mask:0xf bank_mask:0xf
	v_add_f32_e32 v18, 1.0, v18
	v_add_f32_e32 v19, 1.0, v19
	v_add_f32_e32 v20, 1.0, v20
	v_add_f32_e32 v21, 1.0, v21
	v_add_f32_dpp v44, v45, v45 row_mirror row_mask:0xf bank_mask:0xf
	v_add_f32_e32 v22, 1.0, v22
	v_add_f32_e32 v23, 1.0, v23
	v_add_f32_e32 v24, 1.0, v24
	v_add_f32_e32 v25, 1.0, v25
	v_fmamk_f32 v44, v44, 0x3c000000, v218
	v_rcp_f32_e32 v18, v18
	v_rcp_f32_e32 v19, v19
	v_rcp_f32_e32 v20, v20
	v_rcp_f32_e32 v21, v21
	v_rcp_f32_e32 v22, v22
	v_rcp_f32_e32 v23, v23
	v_mul_f32_e32 v45, 0x4b800000, v44
	v_cmp_gt_f32_e32 vcc, s11, v44
	v_rcp_f32_e32 v24, v24
	v_rcp_f32_e32 v25, v25
	v_cndmask_b32_e32 v44, v44, v45, vcc
	v_rsq_f32_e32 v44, v44
	v_pk_mul_f32 v[18:19], v[18:19], v[34:35]
	v_mul_f32_e32 v45, 0x45800000, v44
	v_cndmask_b32_e32 v46, v44, v45, vcc
	v_pk_mul_f32 v[20:21], v[20:21], v[36:37]
	v_pk_mul_f32 v[22:23], v[22:23], v[38:39]
	v_pk_mul_f32 v[24:25], v[24:25], v[40:41]
	v_pk_mul_f32 v[26:27], v[46:47], v[26:27] op_sel_hi:[0,1]
	v_pk_mul_f32 v[28:29], v[46:47], v[28:29] op_sel_hi:[0,1]
	v_pk_mul_f32 v[30:31], v[46:47], v[30:31] op_sel_hi:[0,1]
	v_pk_mul_f32 v[32:33], v[46:47], v[32:33] op_sel_hi:[0,1]
	v_pk_mul_f32 v[26:27], v[0:1], v[26:27]
	v_pk_mul_f32 v[28:29], v[2:3], v[28:29]
	v_pk_mul_f32 v[30:31], v[4:5], v[30:31]
	v_pk_mul_f32 v[32:33], v[6:7], v[32:33]
	v_pk_mul_f32 v[26:27], v[18:19], v[26:27]
	v_pk_mul_f32 v[28:29], v[20:21], v[28:29]
	v_pk_mul_f32 v[30:31], v[22:23], v[30:31]
	v_pk_mul_f32 v[32:33], v[24:25], v[32:33]
	v_cvt_pk_bf16_f32 v92, v26, v27
	v_cvt_pk_bf16_f32 v93, v28, v29
	v_cvt_pk_bf16_f32 v94, v30, v31
	v_cvt_pk_bf16_f32 v95, v32, v33
	global_store_dwordx4 v[50:51], v[92:95], off
	v_lshl_add_u64 v[50:51], v[50:51], 0, s[18:19]
	s_waitcnt vmcnt(24)
	v_lshlrev_b32_e32 v26, 16, v100
	v_and_b32_e32 v27, 0xffff0000, v100
	v_lshlrev_b32_e32 v28, 16, v101
	v_and_b32_e32 v29, 0xffff0000, v101
	v_lshlrev_b32_e32 v30, 16, v102
	v_and_b32_e32 v31, 0xffff0000, v102
	v_lshlrev_b32_e32 v32, 16, v103
	v_and_b32_e32 v33, 0xffff0000, v103
	v_lshlrev_b32_e32 v34, 16, v104
	v_and_b32_e32 v35, 0xffff0000, v104
	v_lshlrev_b32_e32 v36, 16, v105
	v_and_b32_e32 v37, 0xffff0000, v105
	v_lshlrev_b32_e32 v38, 16, v106
	v_and_b32_e32 v39, 0xffff0000, v106
	v_lshlrev_b32_e32 v40, 16, v107
	v_and_b32_e32 v41, 0xffff0000, v107
	v_pk_mul_f32 v[42:43], v[26:27], v[26:27]
	v_add_f32_e32 v44, v42, v43
	v_pk_mul_f32 v[42:43], v[28:29], v[28:29]
	v_add_f32_e32 v44, v42, v44
	v_add_f32_e32 v44, v43, v44
	v_pk_mul_f32 v[42:43], v[30:31], v[30:31]
	v_add_f32_e32 v44, v42, v44
	v_add_f32_e32 v44, v43, v44
	v_pk_mul_f32 v[42:43], v[32:33], v[32:33]
	v_add_f32_e32 v44, v42, v44
	v_add_f32_e32 v44, v43, v44
	v_mul_f32_e32 v18, 0xbfb8aa3b, v34
	v_mul_f32_e32 v19, 0xbfb8aa3b, v35
	v_mul_f32_e32 v20, 0xbfb8aa3b, v36
	v_mul_f32_e32 v21, 0xbfb8aa3b, v37
	v_mul_f32_e32 v22, 0xbfb8aa3b, v38
	v_mul_f32_e32 v23, 0xbfb8aa3b, v39
	v_mul_f32_e32 v24, 0xbfb8aa3b, v40
	v_mul_f32_e32 v25, 0xbfb8aa3b, v41
	v_add_f32_dpp v45, v44, v44 quad_perm:[1,0,3,2] row_mask:0xf bank_mask:0xf
	v_exp_f32_e32 v18, v18
	v_exp_f32_e32 v19, v19
	v_exp_f32_e32 v20, v20
	v_exp_f32_e32 v21, v21
	v_add_f32_dpp v44, v45, v45 quad_perm:[2,3,0,1] row_mask:0xf bank_mask:0xf
	v_exp_f32_e32 v22, v22
	v_exp_f32_e32 v23, v23
	v_exp_f32_e32 v24, v24
	v_exp_f32_e32 v25, v25
	v_add_f32_dpp v45, v44, v44 row_half_mirror row_mask:0xf bank_mask:0xf
	v_add_f32_e32 v18, 1.0, v18
	v_add_f32_e32 v19, 1.0, v19
	v_add_f32_e32 v20, 1.0, v20
	v_add_f32_e32 v21, 1.0, v21
	v_add_f32_dpp v44, v45, v45 row_mirror row_mask:0xf bank_mask:0xf
	v_add_f32_e32 v22, 1.0, v22
	v_add_f32_e32 v23, 1.0, v23
	v_add_f32_e32 v24, 1.0, v24
	v_add_f32_e32 v25, 1.0, v25
	v_fmamk_f32 v44, v44, 0x3c000000, v218
	v_rcp_f32_e32 v18, v18
	v_rcp_f32_e32 v19, v19
	v_rcp_f32_e32 v20, v20
	v_rcp_f32_e32 v21, v21
	v_rcp_f32_e32 v22, v22
	v_rcp_f32_e32 v23, v23
	v_mul_f32_e32 v45, 0x4b800000, v44
	v_cmp_gt_f32_e32 vcc, s11, v44
	v_rcp_f32_e32 v24, v24
	v_rcp_f32_e32 v25, v25
	v_cndmask_b32_e32 v44, v44, v45, vcc
	v_rsq_f32_e32 v44, v44
	v_pk_mul_f32 v[18:19], v[18:19], v[34:35]
	v_mul_f32_e32 v45, 0x45800000, v44
	v_cndmask_b32_e32 v46, v44, v45, vcc
	v_pk_mul_f32 v[20:21], v[20:21], v[36:37]
	v_pk_mul_f32 v[22:23], v[22:23], v[38:39]
	v_pk_mul_f32 v[24:25], v[24:25], v[40:41]
	v_pk_mul_f32 v[26:27], v[46:47], v[26:27] op_sel_hi:[0,1]
	v_pk_mul_f32 v[28:29], v[46:47], v[28:29] op_sel_hi:[0,1]
	v_pk_mul_f32 v[30:31], v[46:47], v[30:31] op_sel_hi:[0,1]
	v_pk_mul_f32 v[32:33], v[46:47], v[32:33] op_sel_hi:[0,1]
	v_pk_mul_f32 v[26:27], v[0:1], v[26:27]
	v_pk_mul_f32 v[28:29], v[2:3], v[28:29]
	v_pk_mul_f32 v[30:31], v[4:5], v[30:31]
	v_pk_mul_f32 v[32:33], v[6:7], v[32:33]
	v_pk_mul_f32 v[26:27], v[18:19], v[26:27]
	v_pk_mul_f32 v[28:29], v[20:21], v[28:29]
	v_pk_mul_f32 v[30:31], v[22:23], v[30:31]
	v_pk_mul_f32 v[32:33], v[24:25], v[32:33]
	v_cvt_pk_bf16_f32 v100, v26, v27
	v_cvt_pk_bf16_f32 v101, v28, v29
	v_cvt_pk_bf16_f32 v102, v30, v31
	v_cvt_pk_bf16_f32 v103, v32, v33
	global_store_dwordx4 v[50:51], v[100:103], off
	v_lshl_add_u64 v[50:51], v[50:51], 0, s[18:19]
	s_waitcnt vmcnt(23)
	v_lshlrev_b32_e32 v26, 16, v108
	v_and_b32_e32 v27, 0xffff0000, v108
	v_lshlrev_b32_e32 v28, 16, v109
	v_and_b32_e32 v29, 0xffff0000, v109
	v_lshlrev_b32_e32 v30, 16, v110
	v_and_b32_e32 v31, 0xffff0000, v110
	v_lshlrev_b32_e32 v32, 16, v111
	v_and_b32_e32 v33, 0xffff0000, v111
	v_lshlrev_b32_e32 v34, 16, v112
	v_and_b32_e32 v35, 0xffff0000, v112
	v_lshlrev_b32_e32 v36, 16, v113
	v_and_b32_e32 v37, 0xffff0000, v113
	v_lshlrev_b32_e32 v38, 16, v114
	v_and_b32_e32 v39, 0xffff0000, v114
	v_lshlrev_b32_e32 v40, 16, v115
	v_and_b32_e32 v41, 0xffff0000, v115
	v_pk_mul_f32 v[42:43], v[26:27], v[26:27]
	v_add_f32_e32 v44, v42, v43
	v_pk_mul_f32 v[42:43], v[28:29], v[28:29]
	v_add_f32_e32 v44, v42, v44
	v_add_f32_e32 v44, v43, v44
	v_pk_mul_f32 v[42:43], v[30:31], v[30:31]
	v_add_f32_e32 v44, v42, v44
	v_add_f32_e32 v44, v43, v44
	v_pk_mul_f32 v[42:43], v[32:33], v[32:33]
	v_add_f32_e32 v44, v42, v44
	v_add_f32_e32 v44, v43, v44
	v_mul_f32_e32 v18, 0xbfb8aa3b, v34
	v_mul_f32_e32 v19, 0xbfb8aa3b, v35
	v_mul_f32_e32 v20, 0xbfb8aa3b, v36
	v_mul_f32_e32 v21, 0xbfb8aa3b, v37
	v_mul_f32_e32 v22, 0xbfb8aa3b, v38
	v_mul_f32_e32 v23, 0xbfb8aa3b, v39
	v_mul_f32_e32 v24, 0xbfb8aa3b, v40
	v_mul_f32_e32 v25, 0xbfb8aa3b, v41
	v_add_f32_dpp v45, v44, v44 quad_perm:[1,0,3,2] row_mask:0xf bank_mask:0xf
	v_exp_f32_e32 v18, v18
	v_exp_f32_e32 v19, v19
	v_exp_f32_e32 v20, v20
	v_exp_f32_e32 v21, v21
	v_add_f32_dpp v44, v45, v45 quad_perm:[2,3,0,1] row_mask:0xf bank_mask:0xf
	v_exp_f32_e32 v22, v22
	v_exp_f32_e32 v23, v23
	v_exp_f32_e32 v24, v24
	v_exp_f32_e32 v25, v25
	v_add_f32_dpp v45, v44, v44 row_half_mirror row_mask:0xf bank_mask:0xf
	v_add_f32_e32 v18, 1.0, v18
	v_add_f32_e32 v19, 1.0, v19
	v_add_f32_e32 v20, 1.0, v20
	v_add_f32_e32 v21, 1.0, v21
	v_add_f32_dpp v44, v45, v45 row_mirror row_mask:0xf bank_mask:0xf
	v_add_f32_e32 v22, 1.0, v22
	v_add_f32_e32 v23, 1.0, v23
	v_add_f32_e32 v24, 1.0, v24
	v_add_f32_e32 v25, 1.0, v25
	v_fmamk_f32 v44, v44, 0x3c000000, v218
	v_rcp_f32_e32 v18, v18
	v_rcp_f32_e32 v19, v19
	v_rcp_f32_e32 v20, v20
	v_rcp_f32_e32 v21, v21
	v_rcp_f32_e32 v22, v22
	v_rcp_f32_e32 v23, v23
	v_mul_f32_e32 v45, 0x4b800000, v44
	v_cmp_gt_f32_e32 vcc, s11, v44
	v_rcp_f32_e32 v24, v24
	v_rcp_f32_e32 v25, v25
	v_cndmask_b32_e32 v44, v44, v45, vcc
	v_rsq_f32_e32 v44, v44
	v_pk_mul_f32 v[18:19], v[18:19], v[34:35]
	v_mul_f32_e32 v45, 0x45800000, v44
	v_cndmask_b32_e32 v46, v44, v45, vcc
	v_pk_mul_f32 v[20:21], v[20:21], v[36:37]
	v_pk_mul_f32 v[22:23], v[22:23], v[38:39]
	v_pk_mul_f32 v[24:25], v[24:25], v[40:41]
	v_pk_mul_f32 v[26:27], v[46:47], v[26:27] op_sel_hi:[0,1]
	v_pk_mul_f32 v[28:29], v[46:47], v[28:29] op_sel_hi:[0,1]
	v_pk_mul_f32 v[30:31], v[46:47], v[30:31] op_sel_hi:[0,1]
	v_pk_mul_f32 v[32:33], v[46:47], v[32:33] op_sel_hi:[0,1]
	v_pk_mul_f32 v[26:27], v[0:1], v[26:27]
	v_pk_mul_f32 v[28:29], v[2:3], v[28:29]
	v_pk_mul_f32 v[30:31], v[4:5], v[30:31]
	v_pk_mul_f32 v[32:33], v[6:7], v[32:33]
	v_pk_mul_f32 v[26:27], v[18:19], v[26:27]
	v_pk_mul_f32 v[28:29], v[20:21], v[28:29]
	v_pk_mul_f32 v[30:31], v[22:23], v[30:31]
	v_pk_mul_f32 v[32:33], v[24:25], v[32:33]
	v_cvt_pk_bf16_f32 v108, v26, v27
	v_cvt_pk_bf16_f32 v109, v28, v29
	v_cvt_pk_bf16_f32 v110, v30, v31
	v_cvt_pk_bf16_f32 v111, v32, v33
	global_store_dwordx4 v[50:51], v[108:111], off
	v_lshl_add_u64 v[50:51], v[50:51], 0, s[18:19]
	s_waitcnt vmcnt(22)
	v_lshlrev_b32_e32 v26, 16, v116
	v_and_b32_e32 v27, 0xffff0000, v116
	v_lshlrev_b32_e32 v28, 16, v117
	v_and_b32_e32 v29, 0xffff0000, v117
	v_lshlrev_b32_e32 v30, 16, v118
	v_and_b32_e32 v31, 0xffff0000, v118
	v_lshlrev_b32_e32 v32, 16, v119
	v_and_b32_e32 v33, 0xffff0000, v119
	v_lshlrev_b32_e32 v34, 16, v120
	v_and_b32_e32 v35, 0xffff0000, v120
	v_lshlrev_b32_e32 v36, 16, v121
	v_and_b32_e32 v37, 0xffff0000, v121
	v_lshlrev_b32_e32 v38, 16, v122
	v_and_b32_e32 v39, 0xffff0000, v122
	v_lshlrev_b32_e32 v40, 16, v123
	v_and_b32_e32 v41, 0xffff0000, v123
	v_pk_mul_f32 v[42:43], v[26:27], v[26:27]
	v_add_f32_e32 v44, v42, v43
	v_pk_mul_f32 v[42:43], v[28:29], v[28:29]
	v_add_f32_e32 v44, v42, v44
	v_add_f32_e32 v44, v43, v44
	v_pk_mul_f32 v[42:43], v[30:31], v[30:31]
	v_add_f32_e32 v44, v42, v44
	v_add_f32_e32 v44, v43, v44
	v_pk_mul_f32 v[42:43], v[32:33], v[32:33]
	v_add_f32_e32 v44, v42, v44
	v_add_f32_e32 v44, v43, v44
	v_mul_f32_e32 v18, 0xbfb8aa3b, v34
	v_mul_f32_e32 v19, 0xbfb8aa3b, v35
	v_mul_f32_e32 v20, 0xbfb8aa3b, v36
	v_mul_f32_e32 v21, 0xbfb8aa3b, v37
	v_mul_f32_e32 v22, 0xbfb8aa3b, v38
	v_mul_f32_e32 v23, 0xbfb8aa3b, v39
	v_mul_f32_e32 v24, 0xbfb8aa3b, v40
	v_mul_f32_e32 v25, 0xbfb8aa3b, v41
	v_add_f32_dpp v45, v44, v44 quad_perm:[1,0,3,2] row_mask:0xf bank_mask:0xf
	v_exp_f32_e32 v18, v18
	v_exp_f32_e32 v19, v19
	v_exp_f32_e32 v20, v20
	v_exp_f32_e32 v21, v21
	v_add_f32_dpp v44, v45, v45 quad_perm:[2,3,0,1] row_mask:0xf bank_mask:0xf
	v_exp_f32_e32 v22, v22
	v_exp_f32_e32 v23, v23
	v_exp_f32_e32 v24, v24
	v_exp_f32_e32 v25, v25
	v_add_f32_dpp v45, v44, v44 row_half_mirror row_mask:0xf bank_mask:0xf
	v_add_f32_e32 v18, 1.0, v18
	v_add_f32_e32 v19, 1.0, v19
	v_add_f32_e32 v20, 1.0, v20
	v_add_f32_e32 v21, 1.0, v21
	v_add_f32_dpp v44, v45, v45 row_mirror row_mask:0xf bank_mask:0xf
	v_add_f32_e32 v22, 1.0, v22
	v_add_f32_e32 v23, 1.0, v23
	v_add_f32_e32 v24, 1.0, v24
	v_add_f32_e32 v25, 1.0, v25
	v_fmamk_f32 v44, v44, 0x3c000000, v218
	v_rcp_f32_e32 v18, v18
	v_rcp_f32_e32 v19, v19
	v_rcp_f32_e32 v20, v20
	v_rcp_f32_e32 v21, v21
	v_rcp_f32_e32 v22, v22
	v_rcp_f32_e32 v23, v23
	v_mul_f32_e32 v45, 0x4b800000, v44
	v_cmp_gt_f32_e32 vcc, s11, v44
	v_rcp_f32_e32 v24, v24
	v_rcp_f32_e32 v25, v25
	v_cndmask_b32_e32 v44, v44, v45, vcc
	v_rsq_f32_e32 v44, v44
	v_pk_mul_f32 v[18:19], v[18:19], v[34:35]
	v_mul_f32_e32 v45, 0x45800000, v44
	v_cndmask_b32_e32 v46, v44, v45, vcc
	v_pk_mul_f32 v[20:21], v[20:21], v[36:37]
	v_pk_mul_f32 v[22:23], v[22:23], v[38:39]
	v_pk_mul_f32 v[24:25], v[24:25], v[40:41]
	v_pk_mul_f32 v[26:27], v[46:47], v[26:27] op_sel_hi:[0,1]
	v_pk_mul_f32 v[28:29], v[46:47], v[28:29] op_sel_hi:[0,1]
	v_pk_mul_f32 v[30:31], v[46:47], v[30:31] op_sel_hi:[0,1]
	v_pk_mul_f32 v[32:33], v[46:47], v[32:33] op_sel_hi:[0,1]
	v_pk_mul_f32 v[26:27], v[0:1], v[26:27]
	v_pk_mul_f32 v[28:29], v[2:3], v[28:29]
	v_pk_mul_f32 v[30:31], v[4:5], v[30:31]
	v_pk_mul_f32 v[32:33], v[6:7], v[32:33]
	v_pk_mul_f32 v[26:27], v[18:19], v[26:27]
	v_pk_mul_f32 v[28:29], v[20:21], v[28:29]
	v_pk_mul_f32 v[30:31], v[22:23], v[30:31]
	v_pk_mul_f32 v[32:33], v[24:25], v[32:33]
	v_cvt_pk_bf16_f32 v116, v26, v27
	v_cvt_pk_bf16_f32 v117, v28, v29
	v_cvt_pk_bf16_f32 v118, v30, v31
	v_cvt_pk_bf16_f32 v119, v32, v33
	global_store_dwordx4 v[50:51], v[116:119], off
	v_lshl_add_u64 v[50:51], v[50:51], 0, s[18:19]
	s_waitcnt vmcnt(21)
	v_lshlrev_b32_e32 v26, 16, v124
	v_and_b32_e32 v27, 0xffff0000, v124
	v_lshlrev_b32_e32 v28, 16, v125
	v_and_b32_e32 v29, 0xffff0000, v125
	v_lshlrev_b32_e32 v30, 16, v126
	v_and_b32_e32 v31, 0xffff0000, v126
	v_lshlrev_b32_e32 v32, 16, v127
	v_and_b32_e32 v33, 0xffff0000, v127
	v_lshlrev_b32_e32 v34, 16, v128
	v_and_b32_e32 v35, 0xffff0000, v128
	v_lshlrev_b32_e32 v36, 16, v129
	v_and_b32_e32 v37, 0xffff0000, v129
	v_lshlrev_b32_e32 v38, 16, v130
	v_and_b32_e32 v39, 0xffff0000, v130
	v_lshlrev_b32_e32 v40, 16, v131
	v_and_b32_e32 v41, 0xffff0000, v131
	v_pk_mul_f32 v[42:43], v[26:27], v[26:27]
	v_add_f32_e32 v44, v42, v43
	v_pk_mul_f32 v[42:43], v[28:29], v[28:29]
	v_add_f32_e32 v44, v42, v44
	v_add_f32_e32 v44, v43, v44
	v_pk_mul_f32 v[42:43], v[30:31], v[30:31]
	v_add_f32_e32 v44, v42, v44
	v_add_f32_e32 v44, v43, v44
	v_pk_mul_f32 v[42:43], v[32:33], v[32:33]
	v_add_f32_e32 v44, v42, v44
	v_add_f32_e32 v44, v43, v44
	v_mul_f32_e32 v18, 0xbfb8aa3b, v34
	v_mul_f32_e32 v19, 0xbfb8aa3b, v35
	v_mul_f32_e32 v20, 0xbfb8aa3b, v36
	v_mul_f32_e32 v21, 0xbfb8aa3b, v37
	v_mul_f32_e32 v22, 0xbfb8aa3b, v38
	v_mul_f32_e32 v23, 0xbfb8aa3b, v39
	v_mul_f32_e32 v24, 0xbfb8aa3b, v40
	v_mul_f32_e32 v25, 0xbfb8aa3b, v41
	v_add_f32_dpp v45, v44, v44 quad_perm:[1,0,3,2] row_mask:0xf bank_mask:0xf
	v_exp_f32_e32 v18, v18
	v_exp_f32_e32 v19, v19
	v_exp_f32_e32 v20, v20
	v_exp_f32_e32 v21, v21
	v_add_f32_dpp v44, v45, v45 quad_perm:[2,3,0,1] row_mask:0xf bank_mask:0xf
	v_exp_f32_e32 v22, v22
	v_exp_f32_e32 v23, v23
	v_exp_f32_e32 v24, v24
	v_exp_f32_e32 v25, v25
	v_add_f32_dpp v45, v44, v44 row_half_mirror row_mask:0xf bank_mask:0xf
	v_add_f32_e32 v18, 1.0, v18
	v_add_f32_e32 v19, 1.0, v19
	v_add_f32_e32 v20, 1.0, v20
	v_add_f32_e32 v21, 1.0, v21
	v_add_f32_dpp v44, v45, v45 row_mirror row_mask:0xf bank_mask:0xf
	v_add_f32_e32 v22, 1.0, v22
	v_add_f32_e32 v23, 1.0, v23
	v_add_f32_e32 v24, 1.0, v24
	v_add_f32_e32 v25, 1.0, v25
	v_fmamk_f32 v44, v44, 0x3c000000, v218
	v_rcp_f32_e32 v18, v18
	v_rcp_f32_e32 v19, v19
	v_rcp_f32_e32 v20, v20
	v_rcp_f32_e32 v21, v21
	v_rcp_f32_e32 v22, v22
	v_rcp_f32_e32 v23, v23
	v_mul_f32_e32 v45, 0x4b800000, v44
	v_cmp_gt_f32_e32 vcc, s11, v44
	v_rcp_f32_e32 v24, v24
	v_rcp_f32_e32 v25, v25
	v_cndmask_b32_e32 v44, v44, v45, vcc
	v_rsq_f32_e32 v44, v44
	v_pk_mul_f32 v[18:19], v[18:19], v[34:35]
	v_mul_f32_e32 v45, 0x45800000, v44
	v_cndmask_b32_e32 v46, v44, v45, vcc
	v_pk_mul_f32 v[20:21], v[20:21], v[36:37]
	v_pk_mul_f32 v[22:23], v[22:23], v[38:39]
	v_pk_mul_f32 v[24:25], v[24:25], v[40:41]
	v_pk_mul_f32 v[26:27], v[46:47], v[26:27] op_sel_hi:[0,1]
	v_pk_mul_f32 v[28:29], v[46:47], v[28:29] op_sel_hi:[0,1]
	v_pk_mul_f32 v[30:31], v[46:47], v[30:31] op_sel_hi:[0,1]
	v_pk_mul_f32 v[32:33], v[46:47], v[32:33] op_sel_hi:[0,1]
	v_pk_mul_f32 v[26:27], v[0:1], v[26:27]
	v_pk_mul_f32 v[28:29], v[2:3], v[28:29]
	v_pk_mul_f32 v[30:31], v[4:5], v[30:31]
	v_pk_mul_f32 v[32:33], v[6:7], v[32:33]
	v_pk_mul_f32 v[26:27], v[18:19], v[26:27]
	v_pk_mul_f32 v[28:29], v[20:21], v[28:29]
	v_pk_mul_f32 v[30:31], v[22:23], v[30:31]
	v_pk_mul_f32 v[32:33], v[24:25], v[32:33]
	v_cvt_pk_bf16_f32 v124, v26, v27
	v_cvt_pk_bf16_f32 v125, v28, v29
	v_cvt_pk_bf16_f32 v126, v30, v31
	v_cvt_pk_bf16_f32 v127, v32, v33
	global_store_dwordx4 v[50:51], v[124:127], off
	v_lshl_add_u64 v[50:51], v[50:51], 0, s[18:19]
	s_waitcnt vmcnt(20)
	v_lshlrev_b32_e32 v26, 16, v132
	v_and_b32_e32 v27, 0xffff0000, v132
	v_lshlrev_b32_e32 v28, 16, v133
	v_and_b32_e32 v29, 0xffff0000, v133
	v_lshlrev_b32_e32 v30, 16, v134
	v_and_b32_e32 v31, 0xffff0000, v134
	v_lshlrev_b32_e32 v32, 16, v135
	v_and_b32_e32 v33, 0xffff0000, v135
	v_lshlrev_b32_e32 v34, 16, v136
	v_and_b32_e32 v35, 0xffff0000, v136
	v_lshlrev_b32_e32 v36, 16, v137
	v_and_b32_e32 v37, 0xffff0000, v137
	v_lshlrev_b32_e32 v38, 16, v138
	v_and_b32_e32 v39, 0xffff0000, v138
	v_lshlrev_b32_e32 v40, 16, v139
	v_and_b32_e32 v41, 0xffff0000, v139
	v_pk_mul_f32 v[42:43], v[26:27], v[26:27]
	v_add_f32_e32 v44, v42, v43
	v_pk_mul_f32 v[42:43], v[28:29], v[28:29]
	v_add_f32_e32 v44, v42, v44
	v_add_f32_e32 v44, v43, v44
	v_pk_mul_f32 v[42:43], v[30:31], v[30:31]
	v_add_f32_e32 v44, v42, v44
	v_add_f32_e32 v44, v43, v44
	v_pk_mul_f32 v[42:43], v[32:33], v[32:33]
	v_add_f32_e32 v44, v42, v44
	v_add_f32_e32 v44, v43, v44
	v_mul_f32_e32 v18, 0xbfb8aa3b, v34
	v_mul_f32_e32 v19, 0xbfb8aa3b, v35
	v_mul_f32_e32 v20, 0xbfb8aa3b, v36
	v_mul_f32_e32 v21, 0xbfb8aa3b, v37
	v_mul_f32_e32 v22, 0xbfb8aa3b, v38
	v_mul_f32_e32 v23, 0xbfb8aa3b, v39
	v_mul_f32_e32 v24, 0xbfb8aa3b, v40
	v_mul_f32_e32 v25, 0xbfb8aa3b, v41
	v_add_f32_dpp v45, v44, v44 quad_perm:[1,0,3,2] row_mask:0xf bank_mask:0xf
	v_exp_f32_e32 v18, v18
	v_exp_f32_e32 v19, v19
	v_exp_f32_e32 v20, v20
	v_exp_f32_e32 v21, v21
	v_add_f32_dpp v44, v45, v45 quad_perm:[2,3,0,1] row_mask:0xf bank_mask:0xf
	v_exp_f32_e32 v22, v22
	v_exp_f32_e32 v23, v23
	v_exp_f32_e32 v24, v24
	v_exp_f32_e32 v25, v25
	v_add_f32_dpp v45, v44, v44 row_half_mirror row_mask:0xf bank_mask:0xf
	v_add_f32_e32 v18, 1.0, v18
	v_add_f32_e32 v19, 1.0, v19
	v_add_f32_e32 v20, 1.0, v20
	v_add_f32_e32 v21, 1.0, v21
	v_add_f32_dpp v44, v45, v45 row_mirror row_mask:0xf bank_mask:0xf
	v_add_f32_e32 v22, 1.0, v22
	v_add_f32_e32 v23, 1.0, v23
	v_add_f32_e32 v24, 1.0, v24
	v_add_f32_e32 v25, 1.0, v25
	v_fmamk_f32 v44, v44, 0x3c000000, v218
	v_rcp_f32_e32 v18, v18
	v_rcp_f32_e32 v19, v19
	v_rcp_f32_e32 v20, v20
	v_rcp_f32_e32 v21, v21
	v_rcp_f32_e32 v22, v22
	v_rcp_f32_e32 v23, v23
	v_mul_f32_e32 v45, 0x4b800000, v44
	v_cmp_gt_f32_e32 vcc, s11, v44
	v_rcp_f32_e32 v24, v24
	v_rcp_f32_e32 v25, v25
	v_cndmask_b32_e32 v44, v44, v45, vcc
	v_rsq_f32_e32 v44, v44
	v_pk_mul_f32 v[18:19], v[18:19], v[34:35]
	v_mul_f32_e32 v45, 0x45800000, v44
	v_cndmask_b32_e32 v46, v44, v45, vcc
	v_pk_mul_f32 v[20:21], v[20:21], v[36:37]
	v_pk_mul_f32 v[22:23], v[22:23], v[38:39]
	v_pk_mul_f32 v[24:25], v[24:25], v[40:41]
	v_pk_mul_f32 v[26:27], v[46:47], v[26:27] op_sel_hi:[0,1]
	v_pk_mul_f32 v[28:29], v[46:47], v[28:29] op_sel_hi:[0,1]
	v_pk_mul_f32 v[30:31], v[46:47], v[30:31] op_sel_hi:[0,1]
	v_pk_mul_f32 v[32:33], v[46:47], v[32:33] op_sel_hi:[0,1]
	v_pk_mul_f32 v[26:27], v[0:1], v[26:27]
	v_pk_mul_f32 v[28:29], v[2:3], v[28:29]
	v_pk_mul_f32 v[30:31], v[4:5], v[30:31]
	v_pk_mul_f32 v[32:33], v[6:7], v[32:33]
	v_pk_mul_f32 v[26:27], v[18:19], v[26:27]
	v_pk_mul_f32 v[28:29], v[20:21], v[28:29]
	v_pk_mul_f32 v[30:31], v[22:23], v[30:31]
	v_pk_mul_f32 v[32:33], v[24:25], v[32:33]
	v_cvt_pk_bf16_f32 v132, v26, v27
	v_cvt_pk_bf16_f32 v133, v28, v29
	v_cvt_pk_bf16_f32 v134, v30, v31
	v_cvt_pk_bf16_f32 v135, v32, v33
	global_store_dwordx4 v[50:51], v[132:135], off
	v_lshl_add_u64 v[50:51], v[50:51], 0, s[18:19]
	s_waitcnt vmcnt(19)
	v_lshlrev_b32_e32 v26, 16, v140
	v_and_b32_e32 v27, 0xffff0000, v140
	v_lshlrev_b32_e32 v28, 16, v141
	v_and_b32_e32 v29, 0xffff0000, v141
	v_lshlrev_b32_e32 v30, 16, v142
	v_and_b32_e32 v31, 0xffff0000, v142
	v_lshlrev_b32_e32 v32, 16, v143
	v_and_b32_e32 v33, 0xffff0000, v143
	v_lshlrev_b32_e32 v34, 16, v144
	v_and_b32_e32 v35, 0xffff0000, v144
	v_lshlrev_b32_e32 v36, 16, v145
	v_and_b32_e32 v37, 0xffff0000, v145
	v_lshlrev_b32_e32 v38, 16, v146
	v_and_b32_e32 v39, 0xffff0000, v146
	v_lshlrev_b32_e32 v40, 16, v147
	v_and_b32_e32 v41, 0xffff0000, v147
	v_pk_mul_f32 v[42:43], v[26:27], v[26:27]
	v_add_f32_e32 v44, v42, v43
	v_pk_mul_f32 v[42:43], v[28:29], v[28:29]
	v_add_f32_e32 v44, v42, v44
	v_add_f32_e32 v44, v43, v44
	v_pk_mul_f32 v[42:43], v[30:31], v[30:31]
	v_add_f32_e32 v44, v42, v44
	v_add_f32_e32 v44, v43, v44
	v_pk_mul_f32 v[42:43], v[32:33], v[32:33]
	v_add_f32_e32 v44, v42, v44
	v_add_f32_e32 v44, v43, v44
	v_mul_f32_e32 v18, 0xbfb8aa3b, v34
	v_mul_f32_e32 v19, 0xbfb8aa3b, v35
	v_mul_f32_e32 v20, 0xbfb8aa3b, v36
	v_mul_f32_e32 v21, 0xbfb8aa3b, v37
	v_mul_f32_e32 v22, 0xbfb8aa3b, v38
	v_mul_f32_e32 v23, 0xbfb8aa3b, v39
	v_mul_f32_e32 v24, 0xbfb8aa3b, v40
	v_mul_f32_e32 v25, 0xbfb8aa3b, v41
	v_add_f32_dpp v45, v44, v44 quad_perm:[1,0,3,2] row_mask:0xf bank_mask:0xf
	v_exp_f32_e32 v18, v18
	v_exp_f32_e32 v19, v19
	v_exp_f32_e32 v20, v20
	v_exp_f32_e32 v21, v21
	v_add_f32_dpp v44, v45, v45 quad_perm:[2,3,0,1] row_mask:0xf bank_mask:0xf
	v_exp_f32_e32 v22, v22
	v_exp_f32_e32 v23, v23
	v_exp_f32_e32 v24, v24
	v_exp_f32_e32 v25, v25
	v_add_f32_dpp v45, v44, v44 row_half_mirror row_mask:0xf bank_mask:0xf
	v_add_f32_e32 v18, 1.0, v18
	v_add_f32_e32 v19, 1.0, v19
	v_add_f32_e32 v20, 1.0, v20
	v_add_f32_e32 v21, 1.0, v21
	v_add_f32_dpp v44, v45, v45 row_mirror row_mask:0xf bank_mask:0xf
	v_add_f32_e32 v22, 1.0, v22
	v_add_f32_e32 v23, 1.0, v23
	v_add_f32_e32 v24, 1.0, v24
	v_add_f32_e32 v25, 1.0, v25
	v_fmamk_f32 v44, v44, 0x3c000000, v218
	v_rcp_f32_e32 v18, v18
	v_rcp_f32_e32 v19, v19
	v_rcp_f32_e32 v20, v20
	v_rcp_f32_e32 v21, v21
	v_rcp_f32_e32 v22, v22
	v_rcp_f32_e32 v23, v23
	v_mul_f32_e32 v45, 0x4b800000, v44
	v_cmp_gt_f32_e32 vcc, s11, v44
	v_rcp_f32_e32 v24, v24
	v_rcp_f32_e32 v25, v25
	v_cndmask_b32_e32 v44, v44, v45, vcc
	v_rsq_f32_e32 v44, v44
	v_pk_mul_f32 v[18:19], v[18:19], v[34:35]
	v_mul_f32_e32 v45, 0x45800000, v44
	v_cndmask_b32_e32 v46, v44, v45, vcc
	v_pk_mul_f32 v[20:21], v[20:21], v[36:37]
	v_pk_mul_f32 v[22:23], v[22:23], v[38:39]
	v_pk_mul_f32 v[24:25], v[24:25], v[40:41]
	v_pk_mul_f32 v[26:27], v[46:47], v[26:27] op_sel_hi:[0,1]
	v_pk_mul_f32 v[28:29], v[46:47], v[28:29] op_sel_hi:[0,1]
	v_pk_mul_f32 v[30:31], v[46:47], v[30:31] op_sel_hi:[0,1]
	v_pk_mul_f32 v[32:33], v[46:47], v[32:33] op_sel_hi:[0,1]
	v_pk_mul_f32 v[26:27], v[0:1], v[26:27]
	v_pk_mul_f32 v[28:29], v[2:3], v[28:29]
	v_pk_mul_f32 v[30:31], v[4:5], v[30:31]
	v_pk_mul_f32 v[32:33], v[6:7], v[32:33]
	v_pk_mul_f32 v[26:27], v[18:19], v[26:27]
	v_pk_mul_f32 v[28:29], v[20:21], v[28:29]
	v_pk_mul_f32 v[30:31], v[22:23], v[30:31]
	v_pk_mul_f32 v[32:33], v[24:25], v[32:33]
	v_cvt_pk_bf16_f32 v140, v26, v27
	v_cvt_pk_bf16_f32 v141, v28, v29
	v_cvt_pk_bf16_f32 v142, v30, v31
	v_cvt_pk_bf16_f32 v143, v32, v33
	global_store_dwordx4 v[50:51], v[140:143], off
	v_lshl_add_u64 v[50:51], v[50:51], 0, s[18:19]
	s_waitcnt vmcnt(18)
	v_lshlrev_b32_e32 v26, 16, v148
	v_and_b32_e32 v27, 0xffff0000, v148
	v_lshlrev_b32_e32 v28, 16, v149
	v_and_b32_e32 v29, 0xffff0000, v149
	v_lshlrev_b32_e32 v30, 16, v150
	v_and_b32_e32 v31, 0xffff0000, v150
	v_lshlrev_b32_e32 v32, 16, v151
	v_and_b32_e32 v33, 0xffff0000, v151
	v_lshlrev_b32_e32 v34, 16, v152
	v_and_b32_e32 v35, 0xffff0000, v152
	v_lshlrev_b32_e32 v36, 16, v153
	v_and_b32_e32 v37, 0xffff0000, v153
	v_lshlrev_b32_e32 v38, 16, v154
	v_and_b32_e32 v39, 0xffff0000, v154
	v_lshlrev_b32_e32 v40, 16, v155
	v_and_b32_e32 v41, 0xffff0000, v155
	v_pk_mul_f32 v[42:43], v[26:27], v[26:27]
	v_add_f32_e32 v44, v42, v43
	v_pk_mul_f32 v[42:43], v[28:29], v[28:29]
	v_add_f32_e32 v44, v42, v44
	v_add_f32_e32 v44, v43, v44
	v_pk_mul_f32 v[42:43], v[30:31], v[30:31]
	v_add_f32_e32 v44, v42, v44
	v_add_f32_e32 v44, v43, v44
	v_pk_mul_f32 v[42:43], v[32:33], v[32:33]
	v_add_f32_e32 v44, v42, v44
	v_add_f32_e32 v44, v43, v44
	v_mul_f32_e32 v18, 0xbfb8aa3b, v34
	v_mul_f32_e32 v19, 0xbfb8aa3b, v35
	v_mul_f32_e32 v20, 0xbfb8aa3b, v36
	v_mul_f32_e32 v21, 0xbfb8aa3b, v37
	v_mul_f32_e32 v22, 0xbfb8aa3b, v38
	v_mul_f32_e32 v23, 0xbfb8aa3b, v39
	v_mul_f32_e32 v24, 0xbfb8aa3b, v40
	v_mul_f32_e32 v25, 0xbfb8aa3b, v41
	v_add_f32_dpp v45, v44, v44 quad_perm:[1,0,3,2] row_mask:0xf bank_mask:0xf
	v_exp_f32_e32 v18, v18
	v_exp_f32_e32 v19, v19
	v_exp_f32_e32 v20, v20
	v_exp_f32_e32 v21, v21
	v_add_f32_dpp v44, v45, v45 quad_perm:[2,3,0,1] row_mask:0xf bank_mask:0xf
	v_exp_f32_e32 v22, v22
	v_exp_f32_e32 v23, v23
	v_exp_f32_e32 v24, v24
	v_exp_f32_e32 v25, v25
	v_add_f32_dpp v45, v44, v44 row_half_mirror row_mask:0xf bank_mask:0xf
	v_add_f32_e32 v18, 1.0, v18
	v_add_f32_e32 v19, 1.0, v19
	v_add_f32_e32 v20, 1.0, v20
	v_add_f32_e32 v21, 1.0, v21
	v_add_f32_dpp v44, v45, v45 row_mirror row_mask:0xf bank_mask:0xf
	v_add_f32_e32 v22, 1.0, v22
	v_add_f32_e32 v23, 1.0, v23
	v_add_f32_e32 v24, 1.0, v24
	v_add_f32_e32 v25, 1.0, v25
	v_fmamk_f32 v44, v44, 0x3c000000, v218
	v_rcp_f32_e32 v18, v18
	v_rcp_f32_e32 v19, v19
	v_rcp_f32_e32 v20, v20
	v_rcp_f32_e32 v21, v21
	v_rcp_f32_e32 v22, v22
	v_rcp_f32_e32 v23, v23
	v_mul_f32_e32 v45, 0x4b800000, v44
	v_cmp_gt_f32_e32 vcc, s11, v44
	v_rcp_f32_e32 v24, v24
	v_rcp_f32_e32 v25, v25
	v_cndmask_b32_e32 v44, v44, v45, vcc
	v_rsq_f32_e32 v44, v44
	v_pk_mul_f32 v[18:19], v[18:19], v[34:35]
	v_mul_f32_e32 v45, 0x45800000, v44
	v_cndmask_b32_e32 v46, v44, v45, vcc
	v_pk_mul_f32 v[20:21], v[20:21], v[36:37]
	v_pk_mul_f32 v[22:23], v[22:23], v[38:39]
	v_pk_mul_f32 v[24:25], v[24:25], v[40:41]
	v_pk_mul_f32 v[26:27], v[46:47], v[26:27] op_sel_hi:[0,1]
	v_pk_mul_f32 v[28:29], v[46:47], v[28:29] op_sel_hi:[0,1]
	v_pk_mul_f32 v[30:31], v[46:47], v[30:31] op_sel_hi:[0,1]
	v_pk_mul_f32 v[32:33], v[46:47], v[32:33] op_sel_hi:[0,1]
	v_pk_mul_f32 v[26:27], v[0:1], v[26:27]
	v_pk_mul_f32 v[28:29], v[2:3], v[28:29]
	v_pk_mul_f32 v[30:31], v[4:5], v[30:31]
	v_pk_mul_f32 v[32:33], v[6:7], v[32:33]
	v_pk_mul_f32 v[26:27], v[18:19], v[26:27]
	v_pk_mul_f32 v[28:29], v[20:21], v[28:29]
	v_pk_mul_f32 v[30:31], v[22:23], v[30:31]
	v_pk_mul_f32 v[32:33], v[24:25], v[32:33]
	v_cvt_pk_bf16_f32 v148, v26, v27
	v_cvt_pk_bf16_f32 v149, v28, v29
	v_cvt_pk_bf16_f32 v150, v30, v31
	v_cvt_pk_bf16_f32 v151, v32, v33
	global_store_dwordx4 v[50:51], v[148:151], off
	v_lshl_add_u64 v[50:51], v[50:51], 0, s[18:19]
	s_waitcnt vmcnt(17)
	v_lshlrev_b32_e32 v26, 16, v156
	v_and_b32_e32 v27, 0xffff0000, v156
	v_lshlrev_b32_e32 v28, 16, v157
	v_and_b32_e32 v29, 0xffff0000, v157
	v_lshlrev_b32_e32 v30, 16, v158
	v_and_b32_e32 v31, 0xffff0000, v158
	v_lshlrev_b32_e32 v32, 16, v159
	v_and_b32_e32 v33, 0xffff0000, v159
	v_lshlrev_b32_e32 v34, 16, v160
	v_and_b32_e32 v35, 0xffff0000, v160
	v_lshlrev_b32_e32 v36, 16, v161
	v_and_b32_e32 v37, 0xffff0000, v161
	v_lshlrev_b32_e32 v38, 16, v162
	v_and_b32_e32 v39, 0xffff0000, v162
	v_lshlrev_b32_e32 v40, 16, v163
	v_and_b32_e32 v41, 0xffff0000, v163
	v_pk_mul_f32 v[42:43], v[26:27], v[26:27]
	v_add_f32_e32 v44, v42, v43
	v_pk_mul_f32 v[42:43], v[28:29], v[28:29]
	v_add_f32_e32 v44, v42, v44
	v_add_f32_e32 v44, v43, v44
	v_pk_mul_f32 v[42:43], v[30:31], v[30:31]
	v_add_f32_e32 v44, v42, v44
	v_add_f32_e32 v44, v43, v44
	v_pk_mul_f32 v[42:43], v[32:33], v[32:33]
	v_add_f32_e32 v44, v42, v44
	v_add_f32_e32 v44, v43, v44
	v_mul_f32_e32 v18, 0xbfb8aa3b, v34
	v_mul_f32_e32 v19, 0xbfb8aa3b, v35
	v_mul_f32_e32 v20, 0xbfb8aa3b, v36
	v_mul_f32_e32 v21, 0xbfb8aa3b, v37
	v_mul_f32_e32 v22, 0xbfb8aa3b, v38
	v_mul_f32_e32 v23, 0xbfb8aa3b, v39
	v_mul_f32_e32 v24, 0xbfb8aa3b, v40
	v_mul_f32_e32 v25, 0xbfb8aa3b, v41
	v_add_f32_dpp v45, v44, v44 quad_perm:[1,0,3,2] row_mask:0xf bank_mask:0xf
	v_exp_f32_e32 v18, v18
	v_exp_f32_e32 v19, v19
	v_exp_f32_e32 v20, v20
	v_exp_f32_e32 v21, v21
	v_add_f32_dpp v44, v45, v45 quad_perm:[2,3,0,1] row_mask:0xf bank_mask:0xf
	v_exp_f32_e32 v22, v22
	v_exp_f32_e32 v23, v23
	v_exp_f32_e32 v24, v24
	v_exp_f32_e32 v25, v25
	v_add_f32_dpp v45, v44, v44 row_half_mirror row_mask:0xf bank_mask:0xf
	v_add_f32_e32 v18, 1.0, v18
	v_add_f32_e32 v19, 1.0, v19
	v_add_f32_e32 v20, 1.0, v20
	v_add_f32_e32 v21, 1.0, v21
	v_add_f32_dpp v44, v45, v45 row_mirror row_mask:0xf bank_mask:0xf
	v_add_f32_e32 v22, 1.0, v22
	v_add_f32_e32 v23, 1.0, v23
	v_add_f32_e32 v24, 1.0, v24
	v_add_f32_e32 v25, 1.0, v25
	v_fmamk_f32 v44, v44, 0x3c000000, v218
	v_rcp_f32_e32 v18, v18
	v_rcp_f32_e32 v19, v19
	v_rcp_f32_e32 v20, v20
	v_rcp_f32_e32 v21, v21
	v_rcp_f32_e32 v22, v22
	v_rcp_f32_e32 v23, v23
	v_mul_f32_e32 v45, 0x4b800000, v44
	v_cmp_gt_f32_e32 vcc, s11, v44
	v_rcp_f32_e32 v24, v24
	v_rcp_f32_e32 v25, v25
	v_cndmask_b32_e32 v44, v44, v45, vcc
	v_rsq_f32_e32 v44, v44
	v_pk_mul_f32 v[18:19], v[18:19], v[34:35]
	v_mul_f32_e32 v45, 0x45800000, v44
	v_cndmask_b32_e32 v46, v44, v45, vcc
	v_pk_mul_f32 v[20:21], v[20:21], v[36:37]
	v_pk_mul_f32 v[22:23], v[22:23], v[38:39]
	v_pk_mul_f32 v[24:25], v[24:25], v[40:41]
	v_pk_mul_f32 v[26:27], v[46:47], v[26:27] op_sel_hi:[0,1]
	v_pk_mul_f32 v[28:29], v[46:47], v[28:29] op_sel_hi:[0,1]
	v_pk_mul_f32 v[30:31], v[46:47], v[30:31] op_sel_hi:[0,1]
	v_pk_mul_f32 v[32:33], v[46:47], v[32:33] op_sel_hi:[0,1]
	v_pk_mul_f32 v[26:27], v[0:1], v[26:27]
	v_pk_mul_f32 v[28:29], v[2:3], v[28:29]
	v_pk_mul_f32 v[30:31], v[4:5], v[30:31]
	v_pk_mul_f32 v[32:33], v[6:7], v[32:33]
	v_pk_mul_f32 v[26:27], v[18:19], v[26:27]
	v_pk_mul_f32 v[28:29], v[20:21], v[28:29]
	v_pk_mul_f32 v[30:31], v[22:23], v[30:31]
	v_pk_mul_f32 v[32:33], v[24:25], v[32:33]
	v_cvt_pk_bf16_f32 v156, v26, v27
	v_cvt_pk_bf16_f32 v157, v28, v29
	v_cvt_pk_bf16_f32 v158, v30, v31
	v_cvt_pk_bf16_f32 v159, v32, v33
	global_store_dwordx4 v[50:51], v[156:159], off
	v_lshl_add_u64 v[50:51], v[50:51], 0, s[18:19]
	s_waitcnt vmcnt(16)
	v_lshlrev_b32_e32 v26, 16, v180
	v_and_b32_e32 v27, 0xffff0000, v180
	v_lshlrev_b32_e32 v28, 16, v181
	v_and_b32_e32 v29, 0xffff0000, v181
	v_lshlrev_b32_e32 v30, 16, v182
	v_and_b32_e32 v31, 0xffff0000, v182
	v_lshlrev_b32_e32 v32, 16, v183
	v_and_b32_e32 v33, 0xffff0000, v183
	v_lshlrev_b32_e32 v34, 16, v184
	v_and_b32_e32 v35, 0xffff0000, v184
	v_lshlrev_b32_e32 v36, 16, v185
	v_and_b32_e32 v37, 0xffff0000, v185
	v_lshlrev_b32_e32 v38, 16, v186
	v_and_b32_e32 v39, 0xffff0000, v186
	v_lshlrev_b32_e32 v40, 16, v187
	v_and_b32_e32 v41, 0xffff0000, v187
	v_pk_mul_f32 v[42:43], v[26:27], v[26:27]
	v_add_f32_e32 v44, v42, v43
	v_pk_mul_f32 v[42:43], v[28:29], v[28:29]
	v_add_f32_e32 v44, v42, v44
	v_add_f32_e32 v44, v43, v44
	v_pk_mul_f32 v[42:43], v[30:31], v[30:31]
	v_add_f32_e32 v44, v42, v44
	v_add_f32_e32 v44, v43, v44
	v_pk_mul_f32 v[42:43], v[32:33], v[32:33]
	v_add_f32_e32 v44, v42, v44
	v_add_f32_e32 v44, v43, v44
	v_mul_f32_e32 v18, 0xbfb8aa3b, v34
	v_mul_f32_e32 v19, 0xbfb8aa3b, v35
	v_mul_f32_e32 v20, 0xbfb8aa3b, v36
	v_mul_f32_e32 v21, 0xbfb8aa3b, v37
	v_mul_f32_e32 v22, 0xbfb8aa3b, v38
	v_mul_f32_e32 v23, 0xbfb8aa3b, v39
	v_mul_f32_e32 v24, 0xbfb8aa3b, v40
	v_mul_f32_e32 v25, 0xbfb8aa3b, v41
	v_add_f32_dpp v45, v44, v44 quad_perm:[1,0,3,2] row_mask:0xf bank_mask:0xf
	v_exp_f32_e32 v18, v18
	v_exp_f32_e32 v19, v19
	v_exp_f32_e32 v20, v20
	v_exp_f32_e32 v21, v21
	v_add_f32_dpp v44, v45, v45 quad_perm:[2,3,0,1] row_mask:0xf bank_mask:0xf
	v_exp_f32_e32 v22, v22
	v_exp_f32_e32 v23, v23
	v_exp_f32_e32 v24, v24
	v_exp_f32_e32 v25, v25
	v_add_f32_dpp v45, v44, v44 row_half_mirror row_mask:0xf bank_mask:0xf
	v_add_f32_e32 v18, 1.0, v18
	v_add_f32_e32 v19, 1.0, v19
	v_add_f32_e32 v20, 1.0, v20
	v_add_f32_e32 v21, 1.0, v21
	v_add_f32_dpp v44, v45, v45 row_mirror row_mask:0xf bank_mask:0xf
	v_add_f32_e32 v22, 1.0, v22
	v_add_f32_e32 v23, 1.0, v23
	v_add_f32_e32 v24, 1.0, v24
	v_add_f32_e32 v25, 1.0, v25
	v_fmamk_f32 v44, v44, 0x3c000000, v218
	v_rcp_f32_e32 v18, v18
	v_rcp_f32_e32 v19, v19
	v_rcp_f32_e32 v20, v20
	v_rcp_f32_e32 v21, v21
	v_rcp_f32_e32 v22, v22
	v_rcp_f32_e32 v23, v23
	v_mul_f32_e32 v45, 0x4b800000, v44
	v_cmp_gt_f32_e32 vcc, s11, v44
	v_rcp_f32_e32 v24, v24
	v_rcp_f32_e32 v25, v25
	v_cndmask_b32_e32 v44, v44, v45, vcc
	v_rsq_f32_e32 v44, v44
	v_pk_mul_f32 v[18:19], v[18:19], v[34:35]
	v_mul_f32_e32 v45, 0x45800000, v44
	v_cndmask_b32_e32 v46, v44, v45, vcc
	v_pk_mul_f32 v[20:21], v[20:21], v[36:37]
	v_pk_mul_f32 v[22:23], v[22:23], v[38:39]
	v_pk_mul_f32 v[24:25], v[24:25], v[40:41]
	v_pk_mul_f32 v[26:27], v[46:47], v[26:27] op_sel_hi:[0,1]
	v_pk_mul_f32 v[28:29], v[46:47], v[28:29] op_sel_hi:[0,1]
	v_pk_mul_f32 v[30:31], v[46:47], v[30:31] op_sel_hi:[0,1]
	v_pk_mul_f32 v[32:33], v[46:47], v[32:33] op_sel_hi:[0,1]
	v_pk_mul_f32 v[26:27], v[0:1], v[26:27]
	v_pk_mul_f32 v[28:29], v[2:3], v[28:29]
	v_pk_mul_f32 v[30:31], v[4:5], v[30:31]
	v_pk_mul_f32 v[32:33], v[6:7], v[32:33]
	v_pk_mul_f32 v[26:27], v[18:19], v[26:27]
	v_pk_mul_f32 v[28:29], v[20:21], v[28:29]
	v_pk_mul_f32 v[30:31], v[22:23], v[30:31]
	v_pk_mul_f32 v[32:33], v[24:25], v[32:33]
	v_cvt_pk_bf16_f32 v180, v26, v27
	v_cvt_pk_bf16_f32 v181, v28, v29
	v_cvt_pk_bf16_f32 v182, v30, v31
	v_cvt_pk_bf16_f32 v183, v32, v33
	global_store_dwordx4 v[50:51], v[180:183], off
	v_lshl_add_u64 v[50:51], v[50:51], 0, s[18:19]
	s_waitcnt vmcnt(15)
	v_lshlrev_b32_e32 v26, 16, v188
	v_and_b32_e32 v27, 0xffff0000, v188
	v_lshlrev_b32_e32 v28, 16, v189
	v_and_b32_e32 v29, 0xffff0000, v189
	v_lshlrev_b32_e32 v30, 16, v190
	v_and_b32_e32 v31, 0xffff0000, v190
	v_lshlrev_b32_e32 v32, 16, v191
	v_and_b32_e32 v33, 0xffff0000, v191
	v_lshlrev_b32_e32 v34, 16, v192
	v_and_b32_e32 v35, 0xffff0000, v192
	v_lshlrev_b32_e32 v36, 16, v193
	v_and_b32_e32 v37, 0xffff0000, v193
	v_lshlrev_b32_e32 v38, 16, v194
	v_and_b32_e32 v39, 0xffff0000, v194
	v_lshlrev_b32_e32 v40, 16, v195
	v_and_b32_e32 v41, 0xffff0000, v195
	v_pk_mul_f32 v[42:43], v[26:27], v[26:27]
	v_add_f32_e32 v44, v42, v43
	v_pk_mul_f32 v[42:43], v[28:29], v[28:29]
	v_add_f32_e32 v44, v42, v44
	v_add_f32_e32 v44, v43, v44
	v_pk_mul_f32 v[42:43], v[30:31], v[30:31]
	v_add_f32_e32 v44, v42, v44
	v_add_f32_e32 v44, v43, v44
	v_pk_mul_f32 v[42:43], v[32:33], v[32:33]
	v_add_f32_e32 v44, v42, v44
	v_add_f32_e32 v44, v43, v44
	v_mul_f32_e32 v18, 0xbfb8aa3b, v34
	v_mul_f32_e32 v19, 0xbfb8aa3b, v35
	v_mul_f32_e32 v20, 0xbfb8aa3b, v36
	v_mul_f32_e32 v21, 0xbfb8aa3b, v37
	v_mul_f32_e32 v22, 0xbfb8aa3b, v38
	v_mul_f32_e32 v23, 0xbfb8aa3b, v39
	v_mul_f32_e32 v24, 0xbfb8aa3b, v40
	v_mul_f32_e32 v25, 0xbfb8aa3b, v41
	v_add_f32_dpp v45, v44, v44 quad_perm:[1,0,3,2] row_mask:0xf bank_mask:0xf
	v_exp_f32_e32 v18, v18
	v_exp_f32_e32 v19, v19
	v_exp_f32_e32 v20, v20
	v_exp_f32_e32 v21, v21
	v_add_f32_dpp v44, v45, v45 quad_perm:[2,3,0,1] row_mask:0xf bank_mask:0xf
	v_exp_f32_e32 v22, v22
	v_exp_f32_e32 v23, v23
	v_exp_f32_e32 v24, v24
	v_exp_f32_e32 v25, v25
	v_add_f32_dpp v45, v44, v44 row_half_mirror row_mask:0xf bank_mask:0xf
	v_add_f32_e32 v18, 1.0, v18
	v_add_f32_e32 v19, 1.0, v19
	v_add_f32_e32 v20, 1.0, v20
	v_add_f32_e32 v21, 1.0, v21
	v_add_f32_dpp v44, v45, v45 row_mirror row_mask:0xf bank_mask:0xf
	v_add_f32_e32 v22, 1.0, v22
	v_add_f32_e32 v23, 1.0, v23
	v_add_f32_e32 v24, 1.0, v24
	v_add_f32_e32 v25, 1.0, v25
	v_fmamk_f32 v44, v44, 0x3c000000, v218
	v_rcp_f32_e32 v18, v18
	v_rcp_f32_e32 v19, v19
	v_rcp_f32_e32 v20, v20
	v_rcp_f32_e32 v21, v21
	v_rcp_f32_e32 v22, v22
	v_rcp_f32_e32 v23, v23
	v_mul_f32_e32 v45, 0x4b800000, v44
	v_cmp_gt_f32_e32 vcc, s11, v44
	v_rcp_f32_e32 v24, v24
	v_rcp_f32_e32 v25, v25
	v_cndmask_b32_e32 v44, v44, v45, vcc
	v_rsq_f32_e32 v44, v44
	v_pk_mul_f32 v[18:19], v[18:19], v[34:35]
	v_mul_f32_e32 v45, 0x45800000, v44
	v_cndmask_b32_e32 v46, v44, v45, vcc
	v_pk_mul_f32 v[20:21], v[20:21], v[36:37]
	v_pk_mul_f32 v[22:23], v[22:23], v[38:39]
	v_pk_mul_f32 v[24:25], v[24:25], v[40:41]
	v_pk_mul_f32 v[26:27], v[46:47], v[26:27] op_sel_hi:[0,1]
	v_pk_mul_f32 v[28:29], v[46:47], v[28:29] op_sel_hi:[0,1]
	v_pk_mul_f32 v[30:31], v[46:47], v[30:31] op_sel_hi:[0,1]
	v_pk_mul_f32 v[32:33], v[46:47], v[32:33] op_sel_hi:[0,1]
	v_pk_mul_f32 v[26:27], v[0:1], v[26:27]
	v_pk_mul_f32 v[28:29], v[2:3], v[28:29]
	v_pk_mul_f32 v[30:31], v[4:5], v[30:31]
	v_pk_mul_f32 v[32:33], v[6:7], v[32:33]
	v_pk_mul_f32 v[26:27], v[18:19], v[26:27]
	v_pk_mul_f32 v[28:29], v[20:21], v[28:29]
	v_pk_mul_f32 v[30:31], v[22:23], v[30:31]
	v_pk_mul_f32 v[32:33], v[24:25], v[32:33]
	v_cvt_pk_bf16_f32 v188, v26, v27
	v_cvt_pk_bf16_f32 v189, v28, v29
	v_cvt_pk_bf16_f32 v190, v30, v31
	v_cvt_pk_bf16_f32 v191, v32, v33
	global_store_dwordx4 v[50:51], v[188:191], off
	s_branch .LBB0_683
